# hyena filter projection: all 64 w3 loads of a column issued up front (shared straight-line body), FMAs in original order
# speedup vs baseline: 1.1263x; 1.0764x over previous
.Lfd_body_0:
	v_mov_b32_e32 v249, 0
	v_mov_b32_e32 v165, 0
	v_mov_b32_e32 v166, 0
	v_mov_b32_e32 v167, 0
	v_mov_b32_e32 v168, 0
	v_mov_b32_e32 v169, 0
	v_mov_b32_e32 v170, 0
	v_mov_b32_e32 v171, 0
	v_mov_b32_e32 v172, 0
	global_load_dword v101, v248, s[98:99]
	s_add_u32 s98, s98, 0x2000
	s_addc_u32 s99, s99, 0
	global_load_dword v102, v248, s[98:99]
	s_add_u32 s98, s98, 0x2000
	s_addc_u32 s99, s99, 0
	global_load_dword v103, v248, s[98:99]
	s_add_u32 s98, s98, 0x2000
	s_addc_u32 s99, s99, 0
	global_load_dword v104, v248, s[98:99]
	s_add_u32 s98, s98, 0x2000
	s_addc_u32 s99, s99, 0
	global_load_dword v105, v248, s[98:99]
	s_add_u32 s98, s98, 0x2000
	s_addc_u32 s99, s99, 0
	global_load_dword v106, v248, s[98:99]
	s_add_u32 s98, s98, 0x2000
	s_addc_u32 s99, s99, 0
	global_load_dword v107, v248, s[98:99]
	s_add_u32 s98, s98, 0x2000
	s_addc_u32 s99, s99, 0
	global_load_dword v108, v248, s[98:99]
	s_add_u32 s98, s98, 0x2000
	s_addc_u32 s99, s99, 0
	global_load_dword v109, v248, s[98:99]
	s_add_u32 s98, s98, 0x2000
	s_addc_u32 s99, s99, 0
	global_load_dword v110, v248, s[98:99]
	s_add_u32 s98, s98, 0x2000
	s_addc_u32 s99, s99, 0
	global_load_dword v111, v248, s[98:99]
	s_add_u32 s98, s98, 0x2000
	s_addc_u32 s99, s99, 0
	global_load_dword v112, v248, s[98:99]
	s_add_u32 s98, s98, 0x2000
	s_addc_u32 s99, s99, 0
	global_load_dword v113, v248, s[98:99]
	s_add_u32 s98, s98, 0x2000
	s_addc_u32 s99, s99, 0
	global_load_dword v114, v248, s[98:99]
	s_add_u32 s98, s98, 0x2000
	s_addc_u32 s99, s99, 0
	global_load_dword v115, v248, s[98:99]
	s_add_u32 s98, s98, 0x2000
	s_addc_u32 s99, s99, 0
	global_load_dword v116, v248, s[98:99]
	s_add_u32 s98, s98, 0x2000
	s_addc_u32 s99, s99, 0
	global_load_dword v117, v248, s[98:99]
	s_add_u32 s98, s98, 0x2000
	s_addc_u32 s99, s99, 0
	global_load_dword v118, v248, s[98:99]
	s_add_u32 s98, s98, 0x2000
	s_addc_u32 s99, s99, 0
	global_load_dword v119, v248, s[98:99]
	s_add_u32 s98, s98, 0x2000
	s_addc_u32 s99, s99, 0
	global_load_dword v120, v248, s[98:99]
	s_add_u32 s98, s98, 0x2000
	s_addc_u32 s99, s99, 0
	global_load_dword v121, v248, s[98:99]
	s_add_u32 s98, s98, 0x2000
	s_addc_u32 s99, s99, 0
	global_load_dword v122, v248, s[98:99]
	s_add_u32 s98, s98, 0x2000
	s_addc_u32 s99, s99, 0
	global_load_dword v123, v248, s[98:99]
	s_add_u32 s98, s98, 0x2000
	s_addc_u32 s99, s99, 0
	global_load_dword v124, v248, s[98:99]
	s_add_u32 s98, s98, 0x2000
	s_addc_u32 s99, s99, 0
	global_load_dword v125, v248, s[98:99]
	s_add_u32 s98, s98, 0x2000
	s_addc_u32 s99, s99, 0
	global_load_dword v126, v248, s[98:99]
	s_add_u32 s98, s98, 0x2000
	s_addc_u32 s99, s99, 0
	global_load_dword v127, v248, s[98:99]
	s_add_u32 s98, s98, 0x2000
	s_addc_u32 s99, s99, 0
	global_load_dword v128, v248, s[98:99]
	s_add_u32 s98, s98, 0x2000
	s_addc_u32 s99, s99, 0
	global_load_dword v129, v248, s[98:99]
	s_add_u32 s98, s98, 0x2000
	s_addc_u32 s99, s99, 0
	global_load_dword v130, v248, s[98:99]
	s_add_u32 s98, s98, 0x2000
	s_addc_u32 s99, s99, 0
	global_load_dword v131, v248, s[98:99]
	s_add_u32 s98, s98, 0x2000
	s_addc_u32 s99, s99, 0
	global_load_dword v132, v248, s[98:99]
	s_add_u32 s98, s98, 0x2000
	s_addc_u32 s99, s99, 0
	global_load_dword v133, v248, s[98:99]
	s_add_u32 s98, s98, 0x2000
	s_addc_u32 s99, s99, 0
	global_load_dword v134, v248, s[98:99]
	s_add_u32 s98, s98, 0x2000
	s_addc_u32 s99, s99, 0
	global_load_dword v135, v248, s[98:99]
	s_add_u32 s98, s98, 0x2000
	s_addc_u32 s99, s99, 0
	global_load_dword v136, v248, s[98:99]
	s_add_u32 s98, s98, 0x2000
	s_addc_u32 s99, s99, 0
	global_load_dword v137, v248, s[98:99]
	s_add_u32 s98, s98, 0x2000
	s_addc_u32 s99, s99, 0
	global_load_dword v138, v248, s[98:99]
	s_add_u32 s98, s98, 0x2000
	s_addc_u32 s99, s99, 0
	global_load_dword v139, v248, s[98:99]
	s_add_u32 s98, s98, 0x2000
	s_addc_u32 s99, s99, 0
	global_load_dword v140, v248, s[98:99]
	s_add_u32 s98, s98, 0x2000
	s_addc_u32 s99, s99, 0
	global_load_dword v141, v248, s[98:99]
	s_add_u32 s98, s98, 0x2000
	s_addc_u32 s99, s99, 0
	global_load_dword v142, v248, s[98:99]
	s_add_u32 s98, s98, 0x2000
	s_addc_u32 s99, s99, 0
	global_load_dword v143, v248, s[98:99]
	s_add_u32 s98, s98, 0x2000
	s_addc_u32 s99, s99, 0
	global_load_dword v144, v248, s[98:99]
	s_add_u32 s98, s98, 0x2000
	s_addc_u32 s99, s99, 0
	global_load_dword v145, v248, s[98:99]
	s_add_u32 s98, s98, 0x2000
	s_addc_u32 s99, s99, 0
	global_load_dword v146, v248, s[98:99]
	s_add_u32 s98, s98, 0x2000
	s_addc_u32 s99, s99, 0
	global_load_dword v147, v248, s[98:99]
	s_add_u32 s98, s98, 0x2000
	s_addc_u32 s99, s99, 0
	global_load_dword v148, v248, s[98:99]
	s_add_u32 s98, s98, 0x2000
	s_addc_u32 s99, s99, 0
	global_load_dword v149, v248, s[98:99]
	s_add_u32 s98, s98, 0x2000
	s_addc_u32 s99, s99, 0
	global_load_dword v150, v248, s[98:99]
	s_add_u32 s98, s98, 0x2000
	s_addc_u32 s99, s99, 0
	global_load_dword v151, v248, s[98:99]
	s_add_u32 s98, s98, 0x2000
	s_addc_u32 s99, s99, 0
	global_load_dword v152, v248, s[98:99]
	s_add_u32 s98, s98, 0x2000
	s_addc_u32 s99, s99, 0
	global_load_dword v153, v248, s[98:99]
	s_add_u32 s98, s98, 0x2000
	s_addc_u32 s99, s99, 0
	global_load_dword v154, v248, s[98:99]
	s_add_u32 s98, s98, 0x2000
	s_addc_u32 s99, s99, 0
	global_load_dword v155, v248, s[98:99]
	s_add_u32 s98, s98, 0x2000
	s_addc_u32 s99, s99, 0
	global_load_dword v156, v248, s[98:99]
	s_add_u32 s98, s98, 0x2000
	s_addc_u32 s99, s99, 0
	global_load_dword v157, v248, s[98:99]
	s_add_u32 s98, s98, 0x2000
	s_addc_u32 s99, s99, 0
	global_load_dword v158, v248, s[98:99]
	s_add_u32 s98, s98, 0x2000
	s_addc_u32 s99, s99, 0
	global_load_dword v159, v248, s[98:99]
	s_add_u32 s98, s98, 0x2000
	s_addc_u32 s99, s99, 0
	global_load_dword v160, v248, s[98:99]
	s_add_u32 s98, s98, 0x2000
	s_addc_u32 s99, s99, 0
	global_load_dword v161, v248, s[98:99]
	s_add_u32 s98, s98, 0x2000
	s_addc_u32 s99, s99, 0
	global_load_dword v162, v248, s[98:99]
	s_add_u32 s98, s98, 0x2000
	s_addc_u32 s99, s99, 0
	global_load_dword v163, v248, s[98:99]
	s_add_u32 s98, s98, 0x2000
	s_addc_u32 s99, s99, 0
	global_load_dword v164, v248, s[98:99]
	ds_read_b128 v[216:219], v249 offset:3104
	ds_read_b128 v[220:223], v249 offset:3360
	ds_read_b128 v[224:227], v249 offset:3616
	ds_read_b128 v[228:231], v249 offset:3872
	ds_read_b128 v[232:235], v249 offset:4128
	ds_read_b128 v[236:239], v249 offset:4384
	ds_read_b128 v[240:243], v249 offset:4640
	ds_read_b128 v[244:247], v249 offset:4896
	s_waitcnt vmcnt(60)
	s_waitcnt lgkmcnt(0)
	v_fmac_f32_e32 v165, v101, v216
	v_fmac_f32_e32 v166, v101, v220
	v_fmac_f32_e32 v167, v101, v224
	v_fmac_f32_e32 v168, v101, v228
	v_fmac_f32_e32 v169, v101, v232
	v_fmac_f32_e32 v170, v101, v236
	v_fmac_f32_e32 v171, v101, v240
	v_fmac_f32_e32 v172, v101, v244
	v_fmac_f32_e32 v165, v102, v217
	v_fmac_f32_e32 v166, v102, v221
	v_fmac_f32_e32 v167, v102, v225
	v_fmac_f32_e32 v168, v102, v229
	v_fmac_f32_e32 v169, v102, v233
	v_fmac_f32_e32 v170, v102, v237
	v_fmac_f32_e32 v171, v102, v241
	v_fmac_f32_e32 v172, v102, v245
	v_fmac_f32_e32 v165, v103, v218
	v_fmac_f32_e32 v166, v103, v222
	v_fmac_f32_e32 v167, v103, v226
	v_fmac_f32_e32 v168, v103, v230
	v_fmac_f32_e32 v169, v103, v234
	v_fmac_f32_e32 v170, v103, v238
	v_fmac_f32_e32 v171, v103, v242
	v_fmac_f32_e32 v172, v103, v246
	v_fmac_f32_e32 v165, v104, v219
	v_fmac_f32_e32 v166, v104, v223
	v_fmac_f32_e32 v167, v104, v227
	v_fmac_f32_e32 v168, v104, v231
	v_fmac_f32_e32 v169, v104, v235
	v_fmac_f32_e32 v170, v104, v239
	v_fmac_f32_e32 v171, v104, v243
	v_fmac_f32_e32 v172, v104, v247
	ds_read_b128 v[216:219], v249 offset:3120
	ds_read_b128 v[220:223], v249 offset:3376
	ds_read_b128 v[224:227], v249 offset:3632
	ds_read_b128 v[228:231], v249 offset:3888
	ds_read_b128 v[232:235], v249 offset:4144
	ds_read_b128 v[236:239], v249 offset:4400
	ds_read_b128 v[240:243], v249 offset:4656
	ds_read_b128 v[244:247], v249 offset:4912
	s_waitcnt vmcnt(56)
	s_waitcnt lgkmcnt(0)
	v_fmac_f32_e32 v165, v105, v216
	v_fmac_f32_e32 v166, v105, v220
	v_fmac_f32_e32 v167, v105, v224
	v_fmac_f32_e32 v168, v105, v228
	v_fmac_f32_e32 v169, v105, v232
	v_fmac_f32_e32 v170, v105, v236
	v_fmac_f32_e32 v171, v105, v240
	v_fmac_f32_e32 v172, v105, v244
	v_fmac_f32_e32 v165, v106, v217
	v_fmac_f32_e32 v166, v106, v221
	v_fmac_f32_e32 v167, v106, v225
	v_fmac_f32_e32 v168, v106, v229
	v_fmac_f32_e32 v169, v106, v233
	v_fmac_f32_e32 v170, v106, v237
	v_fmac_f32_e32 v171, v106, v241
	v_fmac_f32_e32 v172, v106, v245
	v_fmac_f32_e32 v165, v107, v218
	v_fmac_f32_e32 v166, v107, v222
	v_fmac_f32_e32 v167, v107, v226
	v_fmac_f32_e32 v168, v107, v230
	v_fmac_f32_e32 v169, v107, v234
	v_fmac_f32_e32 v170, v107, v238
	v_fmac_f32_e32 v171, v107, v242
	v_fmac_f32_e32 v172, v107, v246
	v_fmac_f32_e32 v165, v108, v219
	v_fmac_f32_e32 v166, v108, v223
	v_fmac_f32_e32 v167, v108, v227
	v_fmac_f32_e32 v168, v108, v231
	v_fmac_f32_e32 v169, v108, v235
	v_fmac_f32_e32 v170, v108, v239
	v_fmac_f32_e32 v171, v108, v243
	v_fmac_f32_e32 v172, v108, v247
	ds_read_b128 v[216:219], v249 offset:3136
	ds_read_b128 v[220:223], v249 offset:3392
	ds_read_b128 v[224:227], v249 offset:3648
	ds_read_b128 v[228:231], v249 offset:3904
	ds_read_b128 v[232:235], v249 offset:4160
	ds_read_b128 v[236:239], v249 offset:4416
	ds_read_b128 v[240:243], v249 offset:4672
	ds_read_b128 v[244:247], v249 offset:4928
	s_waitcnt vmcnt(52)
	s_waitcnt lgkmcnt(0)
	v_fmac_f32_e32 v165, v109, v216
	v_fmac_f32_e32 v166, v109, v220
	v_fmac_f32_e32 v167, v109, v224
	v_fmac_f32_e32 v168, v109, v228
	v_fmac_f32_e32 v169, v109, v232
	v_fmac_f32_e32 v170, v109, v236
	v_fmac_f32_e32 v171, v109, v240
	v_fmac_f32_e32 v172, v109, v244
	v_fmac_f32_e32 v165, v110, v217
	v_fmac_f32_e32 v166, v110, v221
	v_fmac_f32_e32 v167, v110, v225
	v_fmac_f32_e32 v168, v110, v229
	v_fmac_f32_e32 v169, v110, v233
	v_fmac_f32_e32 v170, v110, v237
	v_fmac_f32_e32 v171, v110, v241
	v_fmac_f32_e32 v172, v110, v245
	v_fmac_f32_e32 v165, v111, v218
	v_fmac_f32_e32 v166, v111, v222
	v_fmac_f32_e32 v167, v111, v226
	v_fmac_f32_e32 v168, v111, v230
	v_fmac_f32_e32 v169, v111, v234
	v_fmac_f32_e32 v170, v111, v238
	v_fmac_f32_e32 v171, v111, v242
	v_fmac_f32_e32 v172, v111, v246
	v_fmac_f32_e32 v165, v112, v219
	v_fmac_f32_e32 v166, v112, v223
	v_fmac_f32_e32 v167, v112, v227
	v_fmac_f32_e32 v168, v112, v231
	v_fmac_f32_e32 v169, v112, v235
	v_fmac_f32_e32 v170, v112, v239
	v_fmac_f32_e32 v171, v112, v243
	v_fmac_f32_e32 v172, v112, v247
	ds_read_b128 v[216:219], v249 offset:3152
	ds_read_b128 v[220:223], v249 offset:3408
	ds_read_b128 v[224:227], v249 offset:3664
	ds_read_b128 v[228:231], v249 offset:3920
	ds_read_b128 v[232:235], v249 offset:4176
	ds_read_b128 v[236:239], v249 offset:4432
	ds_read_b128 v[240:243], v249 offset:4688
	ds_read_b128 v[244:247], v249 offset:4944
	s_waitcnt vmcnt(48)
	s_waitcnt lgkmcnt(0)
	v_fmac_f32_e32 v165, v113, v216
	v_fmac_f32_e32 v166, v113, v220
	v_fmac_f32_e32 v167, v113, v224
	v_fmac_f32_e32 v168, v113, v228
	v_fmac_f32_e32 v169, v113, v232
	v_fmac_f32_e32 v170, v113, v236
	v_fmac_f32_e32 v171, v113, v240
	v_fmac_f32_e32 v172, v113, v244
	v_fmac_f32_e32 v165, v114, v217
	v_fmac_f32_e32 v166, v114, v221
	v_fmac_f32_e32 v167, v114, v225
	v_fmac_f32_e32 v168, v114, v229
	v_fmac_f32_e32 v169, v114, v233
	v_fmac_f32_e32 v170, v114, v237
	v_fmac_f32_e32 v171, v114, v241
	v_fmac_f32_e32 v172, v114, v245
	v_fmac_f32_e32 v165, v115, v218
	v_fmac_f32_e32 v166, v115, v222
	v_fmac_f32_e32 v167, v115, v226
	v_fmac_f32_e32 v168, v115, v230
	v_fmac_f32_e32 v169, v115, v234
	v_fmac_f32_e32 v170, v115, v238
	v_fmac_f32_e32 v171, v115, v242
	v_fmac_f32_e32 v172, v115, v246
	v_fmac_f32_e32 v165, v116, v219
	v_fmac_f32_e32 v166, v116, v223
	v_fmac_f32_e32 v167, v116, v227
	v_fmac_f32_e32 v168, v116, v231
	v_fmac_f32_e32 v169, v116, v235
	v_fmac_f32_e32 v170, v116, v239
	v_fmac_f32_e32 v171, v116, v243
	v_fmac_f32_e32 v172, v116, v247
	ds_read_b128 v[216:219], v249 offset:3168
	ds_read_b128 v[220:223], v249 offset:3424
	ds_read_b128 v[224:227], v249 offset:3680
	ds_read_b128 v[228:231], v249 offset:3936
	ds_read_b128 v[232:235], v249 offset:4192
	ds_read_b128 v[236:239], v249 offset:4448
	ds_read_b128 v[240:243], v249 offset:4704
	ds_read_b128 v[244:247], v249 offset:4960
	s_waitcnt vmcnt(44)
	s_waitcnt lgkmcnt(0)
	v_fmac_f32_e32 v165, v117, v216
	v_fmac_f32_e32 v166, v117, v220
	v_fmac_f32_e32 v167, v117, v224
	v_fmac_f32_e32 v168, v117, v228
	v_fmac_f32_e32 v169, v117, v232
	v_fmac_f32_e32 v170, v117, v236
	v_fmac_f32_e32 v171, v117, v240
	v_fmac_f32_e32 v172, v117, v244
	v_fmac_f32_e32 v165, v118, v217
	v_fmac_f32_e32 v166, v118, v221
	v_fmac_f32_e32 v167, v118, v225
	v_fmac_f32_e32 v168, v118, v229
	v_fmac_f32_e32 v169, v118, v233
	v_fmac_f32_e32 v170, v118, v237
	v_fmac_f32_e32 v171, v118, v241
	v_fmac_f32_e32 v172, v118, v245
	v_fmac_f32_e32 v165, v119, v218
	v_fmac_f32_e32 v166, v119, v222
	v_fmac_f32_e32 v167, v119, v226
	v_fmac_f32_e32 v168, v119, v230
	v_fmac_f32_e32 v169, v119, v234
	v_fmac_f32_e32 v170, v119, v238
	v_fmac_f32_e32 v171, v119, v242
	v_fmac_f32_e32 v172, v119, v246
	v_fmac_f32_e32 v165, v120, v219
	v_fmac_f32_e32 v166, v120, v223
	v_fmac_f32_e32 v167, v120, v227
	v_fmac_f32_e32 v168, v120, v231
	v_fmac_f32_e32 v169, v120, v235
	v_fmac_f32_e32 v170, v120, v239
	v_fmac_f32_e32 v171, v120, v243
	v_fmac_f32_e32 v172, v120, v247
	ds_read_b128 v[216:219], v249 offset:3184
	ds_read_b128 v[220:223], v249 offset:3440
	ds_read_b128 v[224:227], v249 offset:3696
	ds_read_b128 v[228:231], v249 offset:3952
	ds_read_b128 v[232:235], v249 offset:4208
	ds_read_b128 v[236:239], v249 offset:4464
	ds_read_b128 v[240:243], v249 offset:4720
	ds_read_b128 v[244:247], v249 offset:4976
	s_waitcnt vmcnt(40)
	s_waitcnt lgkmcnt(0)
	v_fmac_f32_e32 v165, v121, v216
	v_fmac_f32_e32 v166, v121, v220
	v_fmac_f32_e32 v167, v121, v224
	v_fmac_f32_e32 v168, v121, v228
	v_fmac_f32_e32 v169, v121, v232
	v_fmac_f32_e32 v170, v121, v236
	v_fmac_f32_e32 v171, v121, v240
	v_fmac_f32_e32 v172, v121, v244
	v_fmac_f32_e32 v165, v122, v217
	v_fmac_f32_e32 v166, v122, v221
	v_fmac_f32_e32 v167, v122, v225
	v_fmac_f32_e32 v168, v122, v229
	v_fmac_f32_e32 v169, v122, v233
	v_fmac_f32_e32 v170, v122, v237
	v_fmac_f32_e32 v171, v122, v241
	v_fmac_f32_e32 v172, v122, v245
	v_fmac_f32_e32 v165, v123, v218
	v_fmac_f32_e32 v166, v123, v222
	v_fmac_f32_e32 v167, v123, v226
	v_fmac_f32_e32 v168, v123, v230
	v_fmac_f32_e32 v169, v123, v234
	v_fmac_f32_e32 v170, v123, v238
	v_fmac_f32_e32 v171, v123, v242
	v_fmac_f32_e32 v172, v123, v246
	v_fmac_f32_e32 v165, v124, v219
	v_fmac_f32_e32 v166, v124, v223
	v_fmac_f32_e32 v167, v124, v227
	v_fmac_f32_e32 v168, v124, v231
	v_fmac_f32_e32 v169, v124, v235
	v_fmac_f32_e32 v170, v124, v239
	v_fmac_f32_e32 v171, v124, v243
	v_fmac_f32_e32 v172, v124, v247
	ds_read_b128 v[216:219], v249 offset:3200
	ds_read_b128 v[220:223], v249 offset:3456
	ds_read_b128 v[224:227], v249 offset:3712
	ds_read_b128 v[228:231], v249 offset:3968
	ds_read_b128 v[232:235], v249 offset:4224
	ds_read_b128 v[236:239], v249 offset:4480
	ds_read_b128 v[240:243], v249 offset:4736
	ds_read_b128 v[244:247], v249 offset:4992
	s_waitcnt vmcnt(36)
	s_waitcnt lgkmcnt(0)
	v_fmac_f32_e32 v165, v125, v216
	v_fmac_f32_e32 v166, v125, v220
	v_fmac_f32_e32 v167, v125, v224
	v_fmac_f32_e32 v168, v125, v228
	v_fmac_f32_e32 v169, v125, v232
	v_fmac_f32_e32 v170, v125, v236
	v_fmac_f32_e32 v171, v125, v240
	v_fmac_f32_e32 v172, v125, v244
	v_fmac_f32_e32 v165, v126, v217
	v_fmac_f32_e32 v166, v126, v221
	v_fmac_f32_e32 v167, v126, v225
	v_fmac_f32_e32 v168, v126, v229
	v_fmac_f32_e32 v169, v126, v233
	v_fmac_f32_e32 v170, v126, v237
	v_fmac_f32_e32 v171, v126, v241
	v_fmac_f32_e32 v172, v126, v245
	v_fmac_f32_e32 v165, v127, v218
	v_fmac_f32_e32 v166, v127, v222
	v_fmac_f32_e32 v167, v127, v226
	v_fmac_f32_e32 v168, v127, v230
	v_fmac_f32_e32 v169, v127, v234
	v_fmac_f32_e32 v170, v127, v238
	v_fmac_f32_e32 v171, v127, v242
	v_fmac_f32_e32 v172, v127, v246
	v_fmac_f32_e32 v165, v128, v219
	v_fmac_f32_e32 v166, v128, v223
	v_fmac_f32_e32 v167, v128, v227
	v_fmac_f32_e32 v168, v128, v231
	v_fmac_f32_e32 v169, v128, v235
	v_fmac_f32_e32 v170, v128, v239
	v_fmac_f32_e32 v171, v128, v243
	v_fmac_f32_e32 v172, v128, v247
	ds_read_b128 v[216:219], v249 offset:3216
	ds_read_b128 v[220:223], v249 offset:3472
	ds_read_b128 v[224:227], v249 offset:3728
	ds_read_b128 v[228:231], v249 offset:3984
	ds_read_b128 v[232:235], v249 offset:4240
	ds_read_b128 v[236:239], v249 offset:4496
	ds_read_b128 v[240:243], v249 offset:4752
	ds_read_b128 v[244:247], v249 offset:5008
	s_waitcnt vmcnt(32)
	s_waitcnt lgkmcnt(0)
	v_fmac_f32_e32 v165, v129, v216
	v_fmac_f32_e32 v166, v129, v220
	v_fmac_f32_e32 v167, v129, v224
	v_fmac_f32_e32 v168, v129, v228
	v_fmac_f32_e32 v169, v129, v232
	v_fmac_f32_e32 v170, v129, v236
	v_fmac_f32_e32 v171, v129, v240
	v_fmac_f32_e32 v172, v129, v244
	v_fmac_f32_e32 v165, v130, v217
	v_fmac_f32_e32 v166, v130, v221
	v_fmac_f32_e32 v167, v130, v225
	v_fmac_f32_e32 v168, v130, v229
	v_fmac_f32_e32 v169, v130, v233
	v_fmac_f32_e32 v170, v130, v237
	v_fmac_f32_e32 v171, v130, v241
	v_fmac_f32_e32 v172, v130, v245
	v_fmac_f32_e32 v165, v131, v218
	v_fmac_f32_e32 v166, v131, v222
	v_fmac_f32_e32 v167, v131, v226
	v_fmac_f32_e32 v168, v131, v230
	v_fmac_f32_e32 v169, v131, v234
	v_fmac_f32_e32 v170, v131, v238
	v_fmac_f32_e32 v171, v131, v242
	v_fmac_f32_e32 v172, v131, v246
	v_fmac_f32_e32 v165, v132, v219
	v_fmac_f32_e32 v166, v132, v223
	v_fmac_f32_e32 v167, v132, v227
	v_fmac_f32_e32 v168, v132, v231
	v_fmac_f32_e32 v169, v132, v235
	v_fmac_f32_e32 v170, v132, v239
	v_fmac_f32_e32 v171, v132, v243
	v_fmac_f32_e32 v172, v132, v247
	ds_read_b128 v[216:219], v249 offset:3232
	ds_read_b128 v[220:223], v249 offset:3488
	ds_read_b128 v[224:227], v249 offset:3744
	ds_read_b128 v[228:231], v249 offset:4000
	ds_read_b128 v[232:235], v249 offset:4256
	ds_read_b128 v[236:239], v249 offset:4512
	ds_read_b128 v[240:243], v249 offset:4768
	ds_read_b128 v[244:247], v249 offset:5024
	s_waitcnt vmcnt(28)
	s_waitcnt lgkmcnt(0)
	v_fmac_f32_e32 v165, v133, v216
	v_fmac_f32_e32 v166, v133, v220
	v_fmac_f32_e32 v167, v133, v224
	v_fmac_f32_e32 v168, v133, v228
	v_fmac_f32_e32 v169, v133, v232
	v_fmac_f32_e32 v170, v133, v236
	v_fmac_f32_e32 v171, v133, v240
	v_fmac_f32_e32 v172, v133, v244
	v_fmac_f32_e32 v165, v134, v217
	v_fmac_f32_e32 v166, v134, v221
	v_fmac_f32_e32 v167, v134, v225
	v_fmac_f32_e32 v168, v134, v229
	v_fmac_f32_e32 v169, v134, v233
	v_fmac_f32_e32 v170, v134, v237
	v_fmac_f32_e32 v171, v134, v241
	v_fmac_f32_e32 v172, v134, v245
	v_fmac_f32_e32 v165, v135, v218
	v_fmac_f32_e32 v166, v135, v222
	v_fmac_f32_e32 v167, v135, v226
	v_fmac_f32_e32 v168, v135, v230
	v_fmac_f32_e32 v169, v135, v234
	v_fmac_f32_e32 v170, v135, v238
	v_fmac_f32_e32 v171, v135, v242
	v_fmac_f32_e32 v172, v135, v246
	v_fmac_f32_e32 v165, v136, v219
	v_fmac_f32_e32 v166, v136, v223
	v_fmac_f32_e32 v167, v136, v227
	v_fmac_f32_e32 v168, v136, v231
	v_fmac_f32_e32 v169, v136, v235
	v_fmac_f32_e32 v170, v136, v239
	v_fmac_f32_e32 v171, v136, v243
	v_fmac_f32_e32 v172, v136, v247
	ds_read_b128 v[216:219], v249 offset:3248
	ds_read_b128 v[220:223], v249 offset:3504
	ds_read_b128 v[224:227], v249 offset:3760
	ds_read_b128 v[228:231], v249 offset:4016
	ds_read_b128 v[232:235], v249 offset:4272
	ds_read_b128 v[236:239], v249 offset:4528
	ds_read_b128 v[240:243], v249 offset:4784
	ds_read_b128 v[244:247], v249 offset:5040
	s_waitcnt vmcnt(24)
	s_waitcnt lgkmcnt(0)
	v_fmac_f32_e32 v165, v137, v216
	v_fmac_f32_e32 v166, v137, v220
	v_fmac_f32_e32 v167, v137, v224
	v_fmac_f32_e32 v168, v137, v228
	v_fmac_f32_e32 v169, v137, v232
	v_fmac_f32_e32 v170, v137, v236
	v_fmac_f32_e32 v171, v137, v240
	v_fmac_f32_e32 v172, v137, v244
	v_fmac_f32_e32 v165, v138, v217
	v_fmac_f32_e32 v166, v138, v221
	v_fmac_f32_e32 v167, v138, v225
	v_fmac_f32_e32 v168, v138, v229
	v_fmac_f32_e32 v169, v138, v233
	v_fmac_f32_e32 v170, v138, v237
	v_fmac_f32_e32 v171, v138, v241
	v_fmac_f32_e32 v172, v138, v245
	v_fmac_f32_e32 v165, v139, v218
	v_fmac_f32_e32 v166, v139, v222
	v_fmac_f32_e32 v167, v139, v226
	v_fmac_f32_e32 v168, v139, v230
	v_fmac_f32_e32 v169, v139, v234
	v_fmac_f32_e32 v170, v139, v238
	v_fmac_f32_e32 v171, v139, v242
	v_fmac_f32_e32 v172, v139, v246
	v_fmac_f32_e32 v165, v140, v219
	v_fmac_f32_e32 v166, v140, v223
	v_fmac_f32_e32 v167, v140, v227
	v_fmac_f32_e32 v168, v140, v231
	v_fmac_f32_e32 v169, v140, v235
	v_fmac_f32_e32 v170, v140, v239
	v_fmac_f32_e32 v171, v140, v243
	v_fmac_f32_e32 v172, v140, v247
	ds_read_b128 v[216:219], v249 offset:3264
	ds_read_b128 v[220:223], v249 offset:3520
	ds_read_b128 v[224:227], v249 offset:3776
	ds_read_b128 v[228:231], v249 offset:4032
	ds_read_b128 v[232:235], v249 offset:4288
	ds_read_b128 v[236:239], v249 offset:4544
	ds_read_b128 v[240:243], v249 offset:4800
	ds_read_b128 v[244:247], v249 offset:5056
	s_waitcnt vmcnt(20)
	s_waitcnt lgkmcnt(0)
	v_fmac_f32_e32 v165, v141, v216
	v_fmac_f32_e32 v166, v141, v220
	v_fmac_f32_e32 v167, v141, v224
	v_fmac_f32_e32 v168, v141, v228
	v_fmac_f32_e32 v169, v141, v232
	v_fmac_f32_e32 v170, v141, v236
	v_fmac_f32_e32 v171, v141, v240
	v_fmac_f32_e32 v172, v141, v244
	v_fmac_f32_e32 v165, v142, v217
	v_fmac_f32_e32 v166, v142, v221
	v_fmac_f32_e32 v167, v142, v225
	v_fmac_f32_e32 v168, v142, v229
	v_fmac_f32_e32 v169, v142, v233
	v_fmac_f32_e32 v170, v142, v237
	v_fmac_f32_e32 v171, v142, v241
	v_fmac_f32_e32 v172, v142, v245
	v_fmac_f32_e32 v165, v143, v218
	v_fmac_f32_e32 v166, v143, v222
	v_fmac_f32_e32 v167, v143, v226
	v_fmac_f32_e32 v168, v143, v230
	v_fmac_f32_e32 v169, v143, v234
	v_fmac_f32_e32 v170, v143, v238
	v_fmac_f32_e32 v171, v143, v242
	v_fmac_f32_e32 v172, v143, v246
	v_fmac_f32_e32 v165, v144, v219
	v_fmac_f32_e32 v166, v144, v223
	v_fmac_f32_e32 v167, v144, v227
	v_fmac_f32_e32 v168, v144, v231
	v_fmac_f32_e32 v169, v144, v235
	v_fmac_f32_e32 v170, v144, v239
	v_fmac_f32_e32 v171, v144, v243
	v_fmac_f32_e32 v172, v144, v247
	ds_read_b128 v[216:219], v249 offset:3280
	ds_read_b128 v[220:223], v249 offset:3536
	ds_read_b128 v[224:227], v249 offset:3792
	ds_read_b128 v[228:231], v249 offset:4048
	ds_read_b128 v[232:235], v249 offset:4304
	ds_read_b128 v[236:239], v249 offset:4560
	ds_read_b128 v[240:243], v249 offset:4816
	ds_read_b128 v[244:247], v249 offset:5072
	s_waitcnt vmcnt(16)
	s_waitcnt lgkmcnt(0)
	v_fmac_f32_e32 v165, v145, v216
	v_fmac_f32_e32 v166, v145, v220
	v_fmac_f32_e32 v167, v145, v224
	v_fmac_f32_e32 v168, v145, v228
	v_fmac_f32_e32 v169, v145, v232
	v_fmac_f32_e32 v170, v145, v236
	v_fmac_f32_e32 v171, v145, v240
	v_fmac_f32_e32 v172, v145, v244
	v_fmac_f32_e32 v165, v146, v217
	v_fmac_f32_e32 v166, v146, v221
	v_fmac_f32_e32 v167, v146, v225
	v_fmac_f32_e32 v168, v146, v229
	v_fmac_f32_e32 v169, v146, v233
	v_fmac_f32_e32 v170, v146, v237
	v_fmac_f32_e32 v171, v146, v241
	v_fmac_f32_e32 v172, v146, v245
	v_fmac_f32_e32 v165, v147, v218
	v_fmac_f32_e32 v166, v147, v222
	v_fmac_f32_e32 v167, v147, v226
	v_fmac_f32_e32 v168, v147, v230
	v_fmac_f32_e32 v169, v147, v234
	v_fmac_f32_e32 v170, v147, v238
	v_fmac_f32_e32 v171, v147, v242
	v_fmac_f32_e32 v172, v147, v246
	v_fmac_f32_e32 v165, v148, v219
	v_fmac_f32_e32 v166, v148, v223
	v_fmac_f32_e32 v167, v148, v227
	v_fmac_f32_e32 v168, v148, v231
	v_fmac_f32_e32 v169, v148, v235
	v_fmac_f32_e32 v170, v148, v239
	v_fmac_f32_e32 v171, v148, v243
	v_fmac_f32_e32 v172, v148, v247
	ds_read_b128 v[216:219], v249 offset:3296
	ds_read_b128 v[220:223], v249 offset:3552
	ds_read_b128 v[224:227], v249 offset:3808
	ds_read_b128 v[228:231], v249 offset:4064
	ds_read_b128 v[232:235], v249 offset:4320
	ds_read_b128 v[236:239], v249 offset:4576
	ds_read_b128 v[240:243], v249 offset:4832
	ds_read_b128 v[244:247], v249 offset:5088
	s_waitcnt vmcnt(12)
	s_waitcnt lgkmcnt(0)
	v_fmac_f32_e32 v165, v149, v216
	v_fmac_f32_e32 v166, v149, v220
	v_fmac_f32_e32 v167, v149, v224
	v_fmac_f32_e32 v168, v149, v228
	v_fmac_f32_e32 v169, v149, v232
	v_fmac_f32_e32 v170, v149, v236
	v_fmac_f32_e32 v171, v149, v240
	v_fmac_f32_e32 v172, v149, v244
	v_fmac_f32_e32 v165, v150, v217
	v_fmac_f32_e32 v166, v150, v221
	v_fmac_f32_e32 v167, v150, v225
	v_fmac_f32_e32 v168, v150, v229
	v_fmac_f32_e32 v169, v150, v233
	v_fmac_f32_e32 v170, v150, v237
	v_fmac_f32_e32 v171, v150, v241
	v_fmac_f32_e32 v172, v150, v245
	v_fmac_f32_e32 v165, v151, v218
	v_fmac_f32_e32 v166, v151, v222
	v_fmac_f32_e32 v167, v151, v226
	v_fmac_f32_e32 v168, v151, v230
	v_fmac_f32_e32 v169, v151, v234
	v_fmac_f32_e32 v170, v151, v238
	v_fmac_f32_e32 v171, v151, v242
	v_fmac_f32_e32 v172, v151, v246
	v_fmac_f32_e32 v165, v152, v219
	v_fmac_f32_e32 v166, v152, v223
	v_fmac_f32_e32 v167, v152, v227
	v_fmac_f32_e32 v168, v152, v231
	v_fmac_f32_e32 v169, v152, v235
	v_fmac_f32_e32 v170, v152, v239
	v_fmac_f32_e32 v171, v152, v243
	v_fmac_f32_e32 v172, v152, v247
	ds_read_b128 v[216:219], v249 offset:3312
	ds_read_b128 v[220:223], v249 offset:3568
	ds_read_b128 v[224:227], v249 offset:3824
	ds_read_b128 v[228:231], v249 offset:4080
	ds_read_b128 v[232:235], v249 offset:4336
	ds_read_b128 v[236:239], v249 offset:4592
	ds_read_b128 v[240:243], v249 offset:4848
	ds_read_b128 v[244:247], v249 offset:5104
	s_waitcnt vmcnt(8)
	s_waitcnt lgkmcnt(0)
	v_fmac_f32_e32 v165, v153, v216
	v_fmac_f32_e32 v166, v153, v220
	v_fmac_f32_e32 v167, v153, v224
	v_fmac_f32_e32 v168, v153, v228
	v_fmac_f32_e32 v169, v153, v232
	v_fmac_f32_e32 v170, v153, v236
	v_fmac_f32_e32 v171, v153, v240
	v_fmac_f32_e32 v172, v153, v244
	v_fmac_f32_e32 v165, v154, v217
	v_fmac_f32_e32 v166, v154, v221
	v_fmac_f32_e32 v167, v154, v225
	v_fmac_f32_e32 v168, v154, v229
	v_fmac_f32_e32 v169, v154, v233
	v_fmac_f32_e32 v170, v154, v237
	v_fmac_f32_e32 v171, v154, v241
	v_fmac_f32_e32 v172, v154, v245
	v_fmac_f32_e32 v165, v155, v218
	v_fmac_f32_e32 v166, v155, v222
	v_fmac_f32_e32 v167, v155, v226
	v_fmac_f32_e32 v168, v155, v230
	v_fmac_f32_e32 v169, v155, v234
	v_fmac_f32_e32 v170, v155, v238
	v_fmac_f32_e32 v171, v155, v242
	v_fmac_f32_e32 v172, v155, v246
	v_fmac_f32_e32 v165, v156, v219
	v_fmac_f32_e32 v166, v156, v223
	v_fmac_f32_e32 v167, v156, v227
	v_fmac_f32_e32 v168, v156, v231
	v_fmac_f32_e32 v169, v156, v235
	v_fmac_f32_e32 v170, v156, v239
	v_fmac_f32_e32 v171, v156, v243
	v_fmac_f32_e32 v172, v156, v247
	ds_read_b128 v[216:219], v249 offset:3328
	ds_read_b128 v[220:223], v249 offset:3584
	ds_read_b128 v[224:227], v249 offset:3840
	ds_read_b128 v[228:231], v249 offset:4096
	ds_read_b128 v[232:235], v249 offset:4352
	ds_read_b128 v[236:239], v249 offset:4608
	ds_read_b128 v[240:243], v249 offset:4864
	ds_read_b128 v[244:247], v249 offset:5120
	s_waitcnt vmcnt(4)
	s_waitcnt lgkmcnt(0)
	v_fmac_f32_e32 v165, v157, v216
	v_fmac_f32_e32 v166, v157, v220
	v_fmac_f32_e32 v167, v157, v224
	v_fmac_f32_e32 v168, v157, v228
	v_fmac_f32_e32 v169, v157, v232
	v_fmac_f32_e32 v170, v157, v236
	v_fmac_f32_e32 v171, v157, v240
	v_fmac_f32_e32 v172, v157, v244
	v_fmac_f32_e32 v165, v158, v217
	v_fmac_f32_e32 v166, v158, v221
	v_fmac_f32_e32 v167, v158, v225
	v_fmac_f32_e32 v168, v158, v229
	v_fmac_f32_e32 v169, v158, v233
	v_fmac_f32_e32 v170, v158, v237
	v_fmac_f32_e32 v171, v158, v241
	v_fmac_f32_e32 v172, v158, v245
	v_fmac_f32_e32 v165, v159, v218
	v_fmac_f32_e32 v166, v159, v222
	v_fmac_f32_e32 v167, v159, v226
	v_fmac_f32_e32 v168, v159, v230
	v_fmac_f32_e32 v169, v159, v234
	v_fmac_f32_e32 v170, v159, v238
	v_fmac_f32_e32 v171, v159, v242
	v_fmac_f32_e32 v172, v159, v246
	v_fmac_f32_e32 v165, v160, v219
	v_fmac_f32_e32 v166, v160, v223
	v_fmac_f32_e32 v167, v160, v227
	v_fmac_f32_e32 v168, v160, v231
	v_fmac_f32_e32 v169, v160, v235
	v_fmac_f32_e32 v170, v160, v239
	v_fmac_f32_e32 v171, v160, v243
	v_fmac_f32_e32 v172, v160, v247
	ds_read_b128 v[216:219], v249 offset:3344
	ds_read_b128 v[220:223], v249 offset:3600
	ds_read_b128 v[224:227], v249 offset:3856
	ds_read_b128 v[228:231], v249 offset:4112
	ds_read_b128 v[232:235], v249 offset:4368
	ds_read_b128 v[236:239], v249 offset:4624
	ds_read_b128 v[240:243], v249 offset:4880
	ds_read_b128 v[244:247], v249 offset:5136
	s_waitcnt vmcnt(0)
	s_waitcnt lgkmcnt(0)
	v_fmac_f32_e32 v165, v161, v216
	v_fmac_f32_e32 v166, v161, v220
	v_fmac_f32_e32 v167, v161, v224
	v_fmac_f32_e32 v168, v161, v228
	v_fmac_f32_e32 v169, v161, v232
	v_fmac_f32_e32 v170, v161, v236
	v_fmac_f32_e32 v171, v161, v240
	v_fmac_f32_e32 v172, v161, v244
	v_fmac_f32_e32 v165, v162, v217
	v_fmac_f32_e32 v166, v162, v221
	v_fmac_f32_e32 v167, v162, v225
	v_fmac_f32_e32 v168, v162, v229
	v_fmac_f32_e32 v169, v162, v233
	v_fmac_f32_e32 v170, v162, v237
	v_fmac_f32_e32 v171, v162, v241
	v_fmac_f32_e32 v172, v162, v245
	v_fmac_f32_e32 v165, v163, v218
	v_fmac_f32_e32 v166, v163, v222
	v_fmac_f32_e32 v167, v163, v226
	v_fmac_f32_e32 v168, v163, v230
	v_fmac_f32_e32 v169, v163, v234
	v_fmac_f32_e32 v170, v163, v238
	v_fmac_f32_e32 v171, v163, v242
	v_fmac_f32_e32 v172, v163, v246
	v_fmac_f32_e32 v165, v164, v219
	v_fmac_f32_e32 v166, v164, v223
	v_fmac_f32_e32 v167, v164, v227
	v_fmac_f32_e32 v168, v164, v231
	v_fmac_f32_e32 v169, v164, v235
	v_fmac_f32_e32 v170, v164, v239
	v_fmac_f32_e32 v171, v164, v243
	v_fmac_f32_e32 v172, v164, v247
	v_readlane_b32 s98, v255, 62
	s_cmp_eq_u32 s98, 0
	s_cbranch_scc1 .Lfd_ret_0_0
	s_cmp_eq_u32 s98, 1
	s_cbranch_scc1 .Lfd_ret_0_1
	s_cmp_eq_u32 s98, 2
	s_cbranch_scc1 .Lfd_ret_0_2
	s_cmp_eq_u32 s98, 3
	s_cbranch_scc1 .Lfd_ret_0_3
	s_cmp_eq_u32 s98, 4
	s_cbranch_scc1 .Lfd_ret_0_4
	s_cmp_eq_u32 s98, 5
	s_cbranch_scc1 .Lfd_ret_0_5
	s_cmp_eq_u32 s98, 6
	s_cbranch_scc1 .Lfd_ret_0_6
	s_branch .Lfd_ret_0_7

.LBB0_169:
	s_or_b64 exec, exec, s[8:9]
	v_ashrrev_i32_e32 v39, 31, v38
	v_lshl_add_u64 v[60:61], v[38:39], 2, s[14:15]
	v_mov_b32_e32 v40, 0
	s_mov_b64 s[0:1], s[62:63]
	s_mov_b64 s[8:9], s[62:63]
	s_movk_i32 s4, 0xc20
	s_mov_b32 s5, 0xfffe0000
	v_mov_b64_e32 v[42:43], v[60:61]
	v_mov_b32_e32 v41, v40
	v_mov_b32_e32 v10, v40
	v_mov_b32_e32 v11, v40
	v_mov_b32_e32 v18, v40
	v_mov_b32_e32 v19, v40
	v_mov_b32_e32 v26, v40
	v_mov_b32_e32 v27, v40
	s_waitcnt lgkmcnt(0)
	s_barrier
	v_lshlrev_b32_e32 v248, 2, v38
	s_mov_b32 s98, 0
	v_writelane_b32 v255, s98, 62
	s_mov_b64 s[98:99], s[14:15]
	s_branch .Lfd_body_0
.Lfd_ret_0_0:
	v_mov_b32_e32 v10, v165
	v_mov_b32_e32 v11, v166
	v_mov_b32_e32 v18, v167
	v_mov_b32_e32 v19, v168
	v_mov_b32_e32 v26, v169
	v_mov_b32_e32 v27, v170
	v_mov_b32_e32 v40, v171
	v_mov_b32_e32 v41, v172
.LBB0_170:
	s_add_i32 s4, s4, 16
	s_mov_b64 s[6:7], 0x8000
	v_lshl_add_u64 v[42:43], v[42:43], 0, s[6:7]
	s_addk_i32 s5, 0x2000
	s_cmp_eq_u32 s5, 0
	s_cbranch_scc0 .LBB0_170
	v_cvt_f32_i32_e32 v2, s52
	s_sub_i32 s4, s55, s52
	s_and_b64 s[6:7], s[16:17], exec
	v_div_scale_f32 v3, s[6:7], v58, v58, -v2
	v_rcp_f32_e32 v4, v3
	v_div_scale_f32 v5, vcc, -v2, v58, -v2
	s_cselect_b32 s6, 0x200000, 0
	v_fma_f32 v6, -v3, v4, 1.0
	v_fmac_f32_e32 v4, v6, v4
	v_mul_f32_e32 v6, v5, v4
	v_fma_f32 v7, -v3, v6, v5
	v_fmac_f32_e32 v6, v7, v4
	v_fma_f32 v3, -v3, v6, v5
	v_div_fmas_f32 v3, v3, v4, v6
	v_div_fixup_f32 v36, v3, v58, -v2
	v_and_b32_e32 v2, 0x1ff, v38
	v_cvt_f32_u32_e32 v3, v2
	s_ashr_i32 s5, s4, 31
	s_add_u32 s0, s0, s6
	s_addc_u32 s1, s1, 0
	v_fmamk_f32 v3, v3, 0x3cc4df2d, v67
	v_mul_f32_e32 v6, v36, v3
	v_mul_f32_e32 v7, 0x3fb8aa3b, v6
	v_fma_f32 v8, v6, s70, -v7
	v_rndne_f32_e32 v9, v7
	v_fmac_f32_e32 v8, 0x32a5705f, v6
	v_sub_f32_e32 v7, v7, v9
	v_add_f32_e32 v7, v7, v8
	s_add_u32 s36, s0, 0x2480000
	v_exp_f32_e32 v7, v7
	v_cvt_i32_f32_e32 v8, v9
	s_addc_u32 s37, s1, 0
	s_lshl_b32 s29, s55, 10
	v_and_b32_e32 v4, 0x200, v38
	v_bfe_i32 v5, v38, 9, 1
	v_cmp_eq_u32_e64 s[6:7], 0, v4
	v_and_b32_e32 v4, s29, v5
	s_cmp_lt_i32 s52, 1
	v_lshlrev_b32_e32 v34, 2, v4
	s_cselect_b64 s[56:57], -1, 0
	s_lshl_b64 s[0:1], s[4:5], 11
	v_lshl_add_u64 v[4:5], s[36:37], 0, v[34:35]
	v_lshlrev_b32_e32 v34, 2, v2
	v_ldexp_f32 v2, v7, v8
	v_cmp_ngt_f32_e32 vcc, s58, v6
	v_writelane_b32 v253, s0, 55
	v_lshl_add_u64 v[42:43], v[4:5], 0, v[34:35]
	v_cndmask_b32_e32 v2, 0, v2, vcc
	v_cmp_nlt_f32_e32 vcc, s12, v6
	v_writelane_b32 v253, s1, 56
	s_movk_i32 s0, 0x3ff
	v_cndmask_b32_e32 v82, v74, v2, vcc
	v_cmp_lt_u32_e64 s[4:5], s0, v38
	v_mul_f32_e32 v4, v82, v10
	s_and_saveexec_b64 s[0:1], s[4:5]
	s_xor_b64 s[0:1], exec, s[0:1]
	s_cbranch_execz .LBB0_177
	s_mov_b64 s[16:17], -1
	s_and_b64 vcc, exec, s[56:57]
	s_cbranch_vccz .LBB0_174
	global_store_dword v[42:43], v35, off
	s_mov_b64 s[16:17], 0

.LBB0_235:
	s_or_b64 exec, exec, s[4:5]
	s_ashr_i32 s55, s54, 31
	s_lshl_b64 s[4:5], s[54:55], 13
	s_add_u32 s4, s8, s4
	s_addc_u32 s5, s9, s5
	v_lshl_add_u64 v[4:5], v[38:39], 2, s[4:5]
	s_mov_b64 s[4:5], 0xe654000
	v_lshl_add_u64 v[40:41], v[4:5], 0, s[4:5]
	v_add_co_u32_e32 v4, vcc, 0xe654000, v4
	v_mov_b32_e32 v62, 0
	s_nop 0
	v_addc_co_u32_e32 v5, vcc, 0, v5, vcc
	s_movk_i32 s8, 0xc20
	s_mov_b64 s[4:5], 0
	v_mov_b32_e32 v63, v62
	v_mov_b32_e32 v10, v62
	v_mov_b32_e32 v11, v62
	v_mov_b32_e32 v18, v62
	v_mov_b32_e32 v19, v62
	v_mov_b32_e32 v26, v62
	v_mov_b32_e32 v27, v62
	global_store_dword v[4:5], v2, off
	v_lshlrev_b32_e32 v248, 2, v38
	v_add_u32_e32 v248, 0x400, v248
	s_mov_b32 s98, 1
	v_writelane_b32 v255, s98, 62
	s_mov_b64 s[98:99], s[14:15]
	s_branch .Lfd_body_0
.Lfd_ret_0_1:
	v_mov_b32_e32 v10, v165
	v_mov_b32_e32 v11, v166
	v_mov_b32_e32 v18, v167
	v_mov_b32_e32 v19, v168
	v_mov_b32_e32 v26, v169
	v_mov_b32_e32 v27, v170
	v_mov_b32_e32 v62, v171
	v_mov_b32_e32 v63, v172
.LBB0_236:
	s_add_i32 s8, s8, 16
	s_add_u32 s4, s4, 0x8000
	s_addc_u32 s5, s5, 0
	s_cmp_lg_u32 s4, 0x80000
	s_cbranch_scc1 .LBB0_236
	v_add_u32_e32 v5, 0x100, v38
	v_and_b32_e32 v6, 0x1ff, v5
	v_cvt_f32_u32_e32 v2, v6
	v_mov_b32_e32 v3, v35
	s_movk_i32 s4, 0x3ff
	v_lshlrev_b32_e32 v6, 2, v6
	v_fmamk_f32 v4, v2, 0x3cc4df2d, v67
	v_bfe_i32 v2, v5, 9, 1
	v_and_b32_e32 v2, s29, v2
	v_lshlrev_b32_e32 v2, 2, v2
	v_lshl_add_u64 v[2:3], s[36:37], 0, v[2:3]
	v_mov_b32_e32 v7, v35
	v_cmp_lt_u32_e64 s[8:9], s4, v5
	v_mul_f32_e32 v5, v36, v4
	v_lshl_add_u64 v[2:3], v[2:3], 0, v[6:7]
	v_mul_f32_e32 v6, 0x3fb8aa3b, v5
	v_fma_f32 v7, v5, s70, -v6
	v_rndne_f32_e32 v8, v6
	v_fmac_f32_e32 v7, 0x32a5705f, v5
	v_sub_f32_e32 v6, v6, v8
	v_add_f32_e32 v6, v6, v7
	v_exp_f32_e32 v6, v6
	v_cvt_i32_f32_e32 v7, v8
	v_cmp_ngt_f32_e32 vcc, s58, v5
	v_ldexp_f32 v6, v6, v7
	s_nop 0
	v_cndmask_b32_e32 v6, 0, v6, vcc
	v_cmp_nlt_f32_e32 vcc, s12, v5
	s_nop 1
	v_cndmask_b32_e32 v5, v74, v6, vcc
	v_mul_f32_e32 v6, v5, v10
	v_cndmask_b32_e64 v5, 0, 1, s[56:57]
	v_cmp_ne_u32_e64 s[4:5], 1, v5
	s_and_saveexec_b64 s[30:31], s[8:9]
	s_xor_b64 s[54:55], exec, s[30:31]
	s_cbranch_execz .LBB0_243
	s_and_b64 vcc, exec, s[4:5]
	s_mov_b64 s[56:57], -1
	s_cbranch_vccnz .LBB0_240
	s_mov_b64 s[56:57], 0
	global_store_dword v[2:3], v35, off

.LBB0_301:
	s_or_b64 exec, exec, s[8:9]
	v_mov_b32_e32 v62, 0
	s_movk_i32 s54, 0xc20
	s_mov_b64 s[8:9], 0
	v_mov_b32_e32 v63, v62
	v_mov_b32_e32 v10, v62
	v_mov_b32_e32 v11, v62
	v_mov_b32_e32 v18, v62
	v_mov_b32_e32 v19, v62
	v_mov_b32_e32 v26, v62
	v_mov_b32_e32 v27, v62
	global_store_dword v[40:41], v5, off offset:1024
	v_lshlrev_b32_e32 v248, 2, v38
	v_add_u32_e32 v248, 0x800, v248
	s_mov_b32 s98, 2
	v_writelane_b32 v255, s98, 62
	s_mov_b64 s[98:99], s[14:15]
	s_branch .Lfd_body_0

.LBB0_302:
	s_add_i32 s54, s54, 16
	s_add_u32 s8, s8, 0x8000
	s_addc_u32 s9, s9, 0
	s_cmp_lg_u32 s8, 0x80000
	s_cbranch_scc1 .LBB0_302
	v_mov_b32_e32 v2, s29
	v_cndmask_b32_e64 v2, 0, v2, s[6:7]
	v_lshlrev_b32_e32 v2, 2, v2
	v_mov_b32_e32 v3, v35
	v_add_u32_e32 v4, 0x200, v38
	v_lshl_add_u64 v[2:3], s[36:37], 0, v[2:3]
	s_movk_i32 s6, 0x3ff
	v_lshl_add_u64 v[2:3], v[2:3], 0, v[34:35]
	v_cmp_lt_u32_e64 s[6:7], s6, v4
	v_mul_f32_e32 v5, v82, v10
	s_and_saveexec_b64 s[8:9], s[6:7]
	s_xor_b64 s[8:9], exec, s[8:9]
	s_cbranch_execz .LBB0_309
	s_and_b64 vcc, exec, s[4:5]
	s_mov_b64 s[54:55], -1
	s_cbranch_vccnz .LBB0_306
	s_mov_b64 s[54:55], 0
	global_store_dword v[2:3], v35, off

.LBB0_367:
	s_or_b64 exec, exec, s[6:7]
	v_mov_b32_e32 v62, 0
	s_movk_i32 s8, 0xc20
	s_mov_b64 s[6:7], 0
	v_mov_b32_e32 v63, v62
	v_mov_b32_e32 v10, v62
	v_mov_b32_e32 v11, v62
	v_mov_b32_e32 v18, v62
	v_mov_b32_e32 v19, v62
	v_mov_b32_e32 v26, v62
	v_mov_b32_e32 v27, v62
	global_store_dword v[40:41], v4, off offset:2048
	v_lshlrev_b32_e32 v248, 2, v38
	v_add_u32_e32 v248, 0xc00, v248
	s_mov_b32 s98, 3
	v_writelane_b32 v255, s98, 62
	s_mov_b64 s[98:99], s[14:15]
	s_branch .Lfd_body_0

.LBB0_368:
	s_add_i32 s8, s8, 16
	s_add_u32 s6, s6, 0x8000
	s_addc_u32 s7, s7, 0
	s_cmp_lg_u32 s6, 0x80000
	s_cbranch_scc1 .LBB0_368
	v_add_u32_e32 v5, 0x300, v38
	v_and_b32_e32 v6, 0x1ff, v5
	v_cvt_f32_u32_e32 v2, v6
	v_mov_b32_e32 v3, v35
	s_movk_i32 s6, 0x3ff
	v_lshlrev_b32_e32 v6, 2, v6
	v_fmamk_f32 v4, v2, 0x3cc4df2d, v67
	v_bfe_i32 v2, v5, 9, 1
	v_and_b32_e32 v2, s29, v2
	v_lshlrev_b32_e32 v2, 2, v2
	v_lshl_add_u64 v[2:3], s[36:37], 0, v[2:3]
	v_mov_b32_e32 v7, v35
	v_cmp_lt_u32_e64 s[6:7], s6, v5
	v_mul_f32_e32 v5, v36, v4
	v_lshl_add_u64 v[2:3], v[2:3], 0, v[6:7]
	v_mul_f32_e32 v6, 0x3fb8aa3b, v5
	v_fma_f32 v7, v5, s70, -v6
	v_rndne_f32_e32 v8, v6
	v_fmac_f32_e32 v7, 0x32a5705f, v5
	v_sub_f32_e32 v6, v6, v8
	v_add_f32_e32 v6, v6, v7
	v_exp_f32_e32 v6, v6
	v_cvt_i32_f32_e32 v7, v8
	v_cmp_ngt_f32_e32 vcc, s58, v5
	v_ldexp_f32 v6, v6, v7
	s_nop 0
	v_cndmask_b32_e32 v6, 0, v6, vcc
	v_cmp_nlt_f32_e32 vcc, s12, v5
	s_nop 1
	v_cndmask_b32_e32 v5, v74, v6, vcc
	v_mul_f32_e32 v6, v5, v10
	s_and_saveexec_b64 s[8:9], s[6:7]
	s_xor_b64 s[8:9], exec, s[8:9]
	s_cbranch_execz .LBB0_375
	s_and_b64 vcc, exec, s[4:5]
	s_mov_b64 s[54:55], -1
	s_cbranch_vccnz .LBB0_372
	s_mov_b64 s[54:55], 0
	global_store_dword v[2:3], v35, off

.LBB0_433:
	s_or_b64 exec, exec, s[6:7]
	v_mov_b32_e32 v60, 0
	s_movk_i32 s6, 0xc20
	s_mov_b32 s7, 0xfffe0000
	v_mov_b32_e32 v61, v60
	v_mov_b32_e32 v10, v60
	v_mov_b32_e32 v11, v60
	v_mov_b32_e32 v18, v60
	v_mov_b32_e32 v19, v60
	v_mov_b32_e32 v26, v60
	v_mov_b32_e32 v27, v60
	global_store_dword v[40:41], v5, off offset:3072
	v_lshlrev_b32_e32 v248, 2, v38
	v_add_u32_e32 v248, 0x1000, v248
	s_mov_b32 s98, 4
	v_writelane_b32 v255, s98, 62
	s_mov_b64 s[98:99], s[14:15]
	s_branch .Lfd_body_0
.Lfd_ret_0_4:
	v_mov_b32_e32 v10, v165
	v_mov_b32_e32 v11, v166
	v_mov_b32_e32 v18, v167
	v_mov_b32_e32 v19, v168
	v_mov_b32_e32 v26, v169
	v_mov_b32_e32 v27, v170
	v_mov_b32_e32 v60, v171
	v_mov_b32_e32 v61, v172
.LBB0_434:
	s_add_i32 s6, s6, 16
	s_addk_i32 s7, 0x2000
	s_cmp_lg_u32 s7, 0
	s_cbranch_scc1 .LBB0_434
	s_movk_i32 s6, 0xfc00
	v_cmp_gt_u32_e64 s[6:7], s6, v38
	v_mul_f32_e32 v3, v82, v10
	s_and_saveexec_b64 s[8:9], s[6:7]
	s_xor_b64 s[8:9], exec, s[8:9]
	s_cbranch_execz .LBB0_441
	s_and_b64 vcc, exec, s[4:5]
	s_mov_b64 s[54:55], -1
	s_cbranch_vccnz .LBB0_438
	s_mov_b64 s[54:55], 0
	global_store_dword v[42:43], v35, off

.LBB0_499:
	s_or_b64 exec, exec, s[6:7]
	v_add_co_u32_e32 v4, vcc, 0x1000, v40
	v_mov_b32_e32 v42, 0
	s_mov_b32 s6, 0
	v_addc_co_u32_e32 v5, vcc, 0, v41, vcc
	v_add_u32_e32 v44, 0x1d00, v38
	v_mov_b32_e32 v43, v42
	v_mov_b32_e32 v10, v42
	v_mov_b32_e32 v11, v42
	v_mov_b32_e32 v18, v42
	v_mov_b32_e32 v19, v42
	v_mov_b32_e32 v26, v42
	v_mov_b32_e32 v27, v42
	global_store_dword v[4:5], v2, off
	v_lshlrev_b32_e32 v248, 2, v38
	v_add_u32_e32 v248, 0x1400, v248
	s_mov_b32 s98, 5
	v_writelane_b32 v255, s98, 62
	s_mov_b64 s[98:99], s[14:15]
	s_branch .Lfd_body_0
.Lfd_ret_0_5:
	v_mov_b32_e32 v10, v165
	v_mov_b32_e32 v11, v166
	v_mov_b32_e32 v18, v167
	v_mov_b32_e32 v19, v168
	v_mov_b32_e32 v26, v169
	v_mov_b32_e32 v27, v170
	v_mov_b32_e32 v42, v171
	v_mov_b32_e32 v43, v172
.LBB0_500:
	s_add_i32 s6, s6, 16
	s_cmpk_lg_i32 s6, 0x100
	v_add_u32_e32 v44, 0x2000, v44
	s_cbranch_scc1 .LBB0_500
	v_add_u32_e32 v4, 0x500, v38
	v_and_b32_e32 v6, 0x1ff, v4
	v_cvt_f32_u32_e32 v2, v6
	v_mov_b32_e32 v3, v35
	s_movk_i32 s6, 0x3ff
	v_lshlrev_b32_e32 v6, 2, v6
	v_fmamk_f32 v5, v2, 0x3cc4df2d, v67
	v_bfe_i32 v2, v4, 9, 1
	v_and_b32_e32 v2, s29, v2
	v_lshlrev_b32_e32 v2, 2, v2
	v_lshl_add_u64 v[2:3], s[36:37], 0, v[2:3]
	v_mov_b32_e32 v7, v35
	v_cmp_lt_u32_e64 s[6:7], s6, v4
	v_mul_f32_e32 v4, v36, v5
	v_lshl_add_u64 v[2:3], v[2:3], 0, v[6:7]
	v_mul_f32_e32 v6, 0x3fb8aa3b, v4
	v_fma_f32 v7, v4, s70, -v6
	v_rndne_f32_e32 v8, v6
	v_fmac_f32_e32 v7, 0x32a5705f, v4
	v_sub_f32_e32 v6, v6, v8
	v_add_f32_e32 v6, v6, v7
	v_exp_f32_e32 v6, v6
	v_cvt_i32_f32_e32 v7, v8
	v_cmp_ngt_f32_e32 vcc, s58, v4
	v_ldexp_f32 v6, v6, v7
	s_nop 0
	v_cndmask_b32_e32 v6, 0, v6, vcc
	v_cmp_nlt_f32_e32 vcc, s12, v4
	s_nop 1
	v_cndmask_b32_e32 v4, v74, v6, vcc
	v_mul_f32_e32 v6, v4, v10
	s_and_saveexec_b64 s[8:9], s[6:7]
	s_xor_b64 s[8:9], exec, s[8:9]
	s_cbranch_execz .LBB0_507
	s_and_b64 vcc, exec, s[4:5]
	s_mov_b64 s[54:55], -1
	s_cbranch_vccnz .LBB0_504
	s_mov_b64 s[54:55], 0
	global_store_dword v[2:3], v35, off

.LBB0_565:
	s_or_b64 exec, exec, s[6:7]
	v_add_co_u32_e32 v2, vcc, 0x1000, v40
	v_mov_b32_e32 v42, 0
	s_mov_b32 s6, 0
	v_addc_co_u32_e32 v3, vcc, 0, v41, vcc
	v_add_u32_e32 v44, 0x1e00, v38
	v_mov_b32_e32 v43, v42
	v_mov_b32_e32 v10, v42
	v_mov_b32_e32 v11, v42
	v_mov_b32_e32 v18, v42
	v_mov_b32_e32 v19, v42
	v_mov_b32_e32 v26, v42
	v_mov_b32_e32 v27, v42
	global_store_dword v[2:3], v4, off offset:1024
	v_lshlrev_b32_e32 v248, 2, v38
	v_add_u32_e32 v248, 0x1800, v248
	s_mov_b32 s98, 6
	v_writelane_b32 v255, s98, 62
	s_mov_b64 s[98:99], s[14:15]
	s_branch .Lfd_body_0

.LBB0_566:
	s_add_i32 s6, s6, 16
	s_cmpk_lg_i32 s6, 0x100
	v_add_u32_e32 v44, 0x2000, v44
	s_cbranch_scc1 .LBB0_566
	v_add_u32_e32 v4, 0x600, v38
	v_bfe_i32 v2, v4, 9, 1
	v_and_b32_e32 v2, s29, v2
	v_lshlrev_b32_e32 v2, 2, v2
	v_mov_b32_e32 v3, v35
	v_lshl_add_u64 v[2:3], s[36:37], 0, v[2:3]
	s_movk_i32 s6, 0x3ff
	v_lshl_add_u64 v[2:3], v[2:3], 0, v[34:35]
	v_cmp_lt_u32_e64 s[6:7], s6, v4
	v_mul_f32_e32 v5, v82, v10
	s_and_saveexec_b64 s[8:9], s[6:7]
	s_xor_b64 s[8:9], exec, s[8:9]
	s_cbranch_execz .LBB0_573
	s_and_b64 vcc, exec, s[4:5]
	s_mov_b64 s[54:55], -1
	s_cbranch_vccnz .LBB0_570
	s_mov_b64 s[54:55], 0
	global_store_dword v[2:3], v35, off

.LBB0_631:
	s_or_b64 exec, exec, s[6:7]
	v_add_co_u32_e32 v2, vcc, 0x1000, v40
	v_mov_b32_e32 v42, 0
	s_mov_b32 s6, 0
	v_addc_co_u32_e32 v3, vcc, 0, v41, vcc
	v_add_u32_e32 v44, 0x1f00, v38
	v_mov_b32_e32 v43, v42
	v_mov_b32_e32 v10, v42
	v_mov_b32_e32 v11, v42
	v_mov_b32_e32 v18, v42
	v_mov_b32_e32 v19, v42
	v_mov_b32_e32 v26, v42
	v_mov_b32_e32 v27, v42
	global_store_dword v[2:3], v4, off offset:2048
	v_lshlrev_b32_e32 v248, 2, v38
	v_add_u32_e32 v248, 0x1c00, v248
	s_mov_b32 s98, 7
	v_writelane_b32 v255, s98, 62
	s_mov_b64 s[98:99], s[14:15]
	s_branch .Lfd_body_0

.LBB0_632:
	s_add_i32 s6, s6, 16
	s_cmpk_lg_i32 s6, 0x100
	v_add_u32_e32 v44, 0x2000, v44
	s_cbranch_scc1 .LBB0_632
	v_add_u32_e32 v4, 0x700, v38
	v_and_b32_e32 v6, 0x1ff, v4
	v_cvt_f32_u32_e32 v2, v6
	s_movk_i32 s6, 0x3ff
	v_cmp_lt_u32_e64 s[6:7], s6, v4
	v_fmamk_f32 v5, v2, 0x3cc4df2d, v67
	v_bfe_i32 v2, v4, 9, 1
	v_and_b32_e32 v2, s29, v2
	v_lshlrev_b32_e32 v34, 2, v2
	v_mul_f32_e32 v4, v36, v5
	v_lshl_add_u64 v[2:3], s[36:37], 0, v[34:35]
	v_lshlrev_b32_e32 v34, 2, v6
	v_mul_f32_e32 v6, 0x3fb8aa3b, v4
	v_fma_f32 v7, v4, s70, -v6
	v_rndne_f32_e32 v8, v6
	v_fmac_f32_e32 v7, 0x32a5705f, v4
	v_sub_f32_e32 v6, v6, v8
	v_add_f32_e32 v6, v6, v7
	v_exp_f32_e32 v6, v6
	v_cvt_i32_f32_e32 v7, v8
	v_cmp_ngt_f32_e32 vcc, s58, v4
	v_lshl_add_u64 v[2:3], v[2:3], 0, v[34:35]
	v_ldexp_f32 v6, v6, v7
	v_cndmask_b32_e32 v6, 0, v6, vcc
	v_cmp_nlt_f32_e32 vcc, s12, v4
	s_nop 1
	v_cndmask_b32_e32 v4, v74, v6, vcc
	v_mul_f32_e32 v6, v4, v10
	s_and_saveexec_b64 s[8:9], s[6:7]
	s_xor_b64 s[8:9], exec, s[8:9]
	s_movk_i32 s29, 0x104
	s_cbranch_execz .LBB0_639
	s_and_b64 vcc, exec, s[4:5]
	s_mov_b64 s[4:5], -1
	s_cbranch_vccnz .LBB0_636
	s_mov_b64 s[4:5], 0
	global_store_dword v[2:3], v35, off

.LBB0_1583:
	v_add_u32_e32 v0, s2, v99
	v_or_b32_e32 v2, v0, v93
	s_lshl_b32 s2, s15, 1
	s_add_u32 s0, s0, s2
	s_addc_u32 s1, s1, 0
	v_ashrrev_i32_e32 v3, 31, v2
	v_lshlrev_b64 v[2:3], 12, v[2:3]
	v_lshl_add_u64 v[2:3], s[0:1], 0, v[2:3]
	v_lshlrev_b32_e32 v0, 1, v95
	v_lshl_add_u64 v[40:41], v[2:3], 0, v[0:1]
	s_movk_i32 s2, 0x1000
	v_add_co_u32_e32 v42, vcc, s2, v40
	v_addc_co_u32_e32 v43, vcc, 0, v41, vcc
	v_add_co_u32_e32 v44, vcc, s2, v42
	v_addc_co_u32_e32 v45, vcc, 0, v43, vcc
	v_add_co_u32_e32 v46, vcc, s2, v44
	v_addc_co_u32_e32 v47, vcc, 0, v45, vcc
	global_load_ushort v48, v[40:41], off offset:3072
	global_load_ushort v49, v[40:41], off offset:3104
	global_load_ushort v50, v[40:41], off offset:3136
	global_load_ushort v51, v[40:41], off offset:3168
	global_load_ushort v52, v[40:41], off offset:3200
	global_load_ushort v53, v[40:41], off offset:3232
	global_load_ushort v54, v[40:41], off offset:3264
	global_load_ushort v55, v[40:41], off offset:3296
	global_load_ushort v56, v[42:43], off offset:3072
	global_load_ushort v57, v[42:43], off offset:3104
	global_load_ushort v58, v[42:43], off offset:3136
	global_load_ushort v59, v[42:43], off offset:3168
	global_load_ushort v60, v[42:43], off offset:3200
	global_load_ushort v61, v[42:43], off offset:3232
	global_load_ushort v62, v[42:43], off offset:3264
	global_load_ushort v63, v[42:43], off offset:3296
	global_load_ushort v64, v[44:45], off offset:3072
	global_load_ushort v65, v[44:45], off offset:3104
	global_load_ushort v66, v[44:45], off offset:3136
	global_load_ushort v67, v[44:45], off offset:3168
	global_load_ushort v68, v[44:45], off offset:3200
	global_load_ushort v69, v[44:45], off offset:3232
	global_load_ushort v70, v[44:45], off offset:3264
	global_load_ushort v71, v[44:45], off offset:3296
	global_load_ushort v72, v[46:47], off offset:3072
	global_load_ushort v73, v[46:47], off offset:3104
	global_load_ushort v74, v[46:47], off offset:3136
	global_load_ushort v75, v[46:47], off offset:3168
	global_load_ushort v76, v[46:47], off offset:3200
	global_load_ushort v77, v[46:47], off offset:3232
	global_load_ushort v78, v[46:47], off offset:3264
	global_load_ushort v3, v[46:47], off offset:3296
	v_add_f32_e32 v100, 0, v8
	v_add_f32_e32 v101, 0, v9
	v_add_f32_e32 v102, 0, v10
	v_add_f32_e32 v103, 0, v11
	v_add_f32_e32 v100, v16, v100
	v_add_f32_e32 v101, v17, v101
	v_add_f32_e32 v102, v18, v102
	v_add_f32_e32 v103, v19, v103
	v_add_f32_e32 v100, v12, v100
	v_add_f32_e32 v101, v13, v101
	v_add_f32_e32 v102, v14, v102
	v_add_f32_e32 v103, v15, v103
	v_add_f32_e32 v100, v36, v100
	v_add_f32_e32 v101, v37, v101
	v_add_f32_e32 v102, v38, v102
	v_add_f32_e32 v103, v39, v103
	v_add_f32_e32 v100, v20, v100
	v_add_f32_e32 v101, v21, v101
	v_add_f32_e32 v102, v22, v102
	v_add_f32_e32 v103, v23, v103
	v_add_f32_e32 v100, v32, v100
	v_add_f32_e32 v101, v33, v101
	v_add_f32_e32 v102, v34, v102
	v_add_f32_e32 v103, v35, v103
	v_add_f32_e32 v100, v24, v100
	v_add_f32_e32 v101, v25, v101
	v_add_f32_e32 v102, v26, v102
	v_add_f32_e32 v103, v27, v103
	v_add_f32_e32 v100, v28, v100
	v_add_f32_e32 v101, v29, v101
	v_add_f32_e32 v102, v30, v102
	v_add_f32_e32 v103, v31, v103
	v_add_f32_dpp v100, v100, v100 quad_perm:[1,0,3,2] row_mask:0xf bank_mask:0xf
	v_add_f32_dpp v101, v101, v101 quad_perm:[1,0,3,2] row_mask:0xf bank_mask:0xf
	v_add_f32_dpp v102, v102, v102 quad_perm:[1,0,3,2] row_mask:0xf bank_mask:0xf
	v_add_f32_dpp v103, v103, v103 quad_perm:[1,0,3,2] row_mask:0xf bank_mask:0xf
	v_add_f32_dpp v100, v100, v100 quad_perm:[2,3,0,1] row_mask:0xf bank_mask:0xf
	v_add_f32_dpp v101, v101, v101 quad_perm:[2,3,0,1] row_mask:0xf bank_mask:0xf
	v_add_f32_dpp v102, v102, v102 quad_perm:[2,3,0,1] row_mask:0xf bank_mask:0xf
	v_add_f32_dpp v103, v103, v103 quad_perm:[2,3,0,1] row_mask:0xf bank_mask:0xf
	v_add_f32_dpp v100, v100, v100 row_half_mirror row_mask:0xf bank_mask:0xf
	v_add_f32_dpp v101, v101, v101 row_half_mirror row_mask:0xf bank_mask:0xf
	v_add_f32_dpp v102, v102, v102 row_half_mirror row_mask:0xf bank_mask:0xf
	v_add_f32_dpp v103, v103, v103 row_half_mirror row_mask:0xf bank_mask:0xf
	v_add_f32_dpp v100, v100, v100 row_mirror row_mask:0xf bank_mask:0xf
	v_add_f32_dpp v101, v101, v101 row_mirror row_mask:0xf bank_mask:0xf
	v_add_f32_dpp v102, v102, v102 row_mirror row_mask:0xf bank_mask:0xf
	v_add_f32_dpp v103, v103, v103 row_mirror row_mask:0xf bank_mask:0xf
	s_brev_b32 s4, 60
	v_mul_f32_e32 v104, s4, v100
	v_mul_f32_e32 v105, s4, v101
	v_mul_f32_e32 v106, s4, v102
	v_mul_f32_e32 v107, s4, v103
	v_sub_f32_e32 v8, v8, v104
	v_sub_f32_e32 v9, v9, v105
	v_sub_f32_e32 v10, v10, v106
	v_sub_f32_e32 v11, v11, v107
	v_sub_f32_e32 v16, v16, v104
	v_sub_f32_e32 v17, v17, v105
	v_sub_f32_e32 v18, v18, v106
	v_sub_f32_e32 v19, v19, v107
	v_sub_f32_e32 v12, v12, v104
	v_sub_f32_e32 v13, v13, v105
	v_sub_f32_e32 v14, v14, v106
	v_sub_f32_e32 v15, v15, v107
	v_sub_f32_e32 v36, v36, v104
	v_sub_f32_e32 v37, v37, v105
	v_sub_f32_e32 v38, v38, v106
	v_sub_f32_e32 v39, v39, v107
	v_sub_f32_e32 v20, v20, v104
	v_sub_f32_e32 v21, v21, v105
	v_sub_f32_e32 v22, v22, v106
	v_sub_f32_e32 v23, v23, v107
	v_sub_f32_e32 v32, v32, v104
	v_sub_f32_e32 v33, v33, v105
	v_sub_f32_e32 v34, v34, v106
	v_sub_f32_e32 v35, v35, v107
	v_sub_f32_e32 v24, v24, v104
	v_sub_f32_e32 v25, v25, v105
	v_sub_f32_e32 v26, v26, v106
	v_sub_f32_e32 v27, v27, v107
	v_sub_f32_e32 v28, v28, v104
	v_sub_f32_e32 v29, v29, v105
	v_sub_f32_e32 v30, v30, v106
	v_sub_f32_e32 v31, v31, v107
	v_mul_f32_e32 v100, v8, v8
	v_mul_f32_e32 v101, v9, v9
	v_mul_f32_e32 v102, v10, v10
	v_mul_f32_e32 v103, v11, v11
	v_fmac_f32_e32 v100, v16, v16
	v_fmac_f32_e32 v101, v17, v17
	v_fmac_f32_e32 v102, v18, v18
	v_fmac_f32_e32 v103, v19, v19
	v_fmac_f32_e32 v100, v12, v12
	v_fmac_f32_e32 v101, v13, v13
	v_fmac_f32_e32 v102, v14, v14
	v_fmac_f32_e32 v103, v15, v15
	v_fmac_f32_e32 v100, v36, v36
	v_fmac_f32_e32 v101, v37, v37
	v_fmac_f32_e32 v102, v38, v38
	v_fmac_f32_e32 v103, v39, v39
	v_fmac_f32_e32 v100, v20, v20
	v_fmac_f32_e32 v101, v21, v21
	v_fmac_f32_e32 v102, v22, v22
	v_fmac_f32_e32 v103, v23, v23
	v_fmac_f32_e32 v100, v32, v32
	v_fmac_f32_e32 v101, v33, v33
	v_fmac_f32_e32 v102, v34, v34
	v_fmac_f32_e32 v103, v35, v35
	v_fmac_f32_e32 v100, v24, v24
	v_fmac_f32_e32 v101, v25, v25
	v_fmac_f32_e32 v102, v26, v26
	v_fmac_f32_e32 v103, v27, v27
	v_fmac_f32_e32 v100, v28, v28
	v_fmac_f32_e32 v101, v29, v29
	v_fmac_f32_e32 v102, v30, v30
	v_fmac_f32_e32 v103, v31, v31
	v_add_f32_dpp v100, v100, v100 quad_perm:[1,0,3,2] row_mask:0xf bank_mask:0xf
	v_add_f32_dpp v101, v101, v101 quad_perm:[1,0,3,2] row_mask:0xf bank_mask:0xf
	v_add_f32_dpp v102, v102, v102 quad_perm:[1,0,3,2] row_mask:0xf bank_mask:0xf
	v_add_f32_dpp v103, v103, v103 quad_perm:[1,0,3,2] row_mask:0xf bank_mask:0xf
	v_add_f32_dpp v100, v100, v100 quad_perm:[2,3,0,1] row_mask:0xf bank_mask:0xf
	v_add_f32_dpp v101, v101, v101 quad_perm:[2,3,0,1] row_mask:0xf bank_mask:0xf
	v_add_f32_dpp v102, v102, v102 quad_perm:[2,3,0,1] row_mask:0xf bank_mask:0xf
	v_add_f32_dpp v103, v103, v103 quad_perm:[2,3,0,1] row_mask:0xf bank_mask:0xf
	v_add_f32_dpp v100, v100, v100 row_half_mirror row_mask:0xf bank_mask:0xf
	v_add_f32_dpp v101, v101, v101 row_half_mirror row_mask:0xf bank_mask:0xf
	v_add_f32_dpp v102, v102, v102 row_half_mirror row_mask:0xf bank_mask:0xf
	v_add_f32_dpp v103, v103, v103 row_half_mirror row_mask:0xf bank_mask:0xf
	v_add_f32_dpp v100, v100, v100 row_mirror row_mask:0xf bank_mask:0xf
	v_add_f32_dpp v101, v101, v101 row_mirror row_mask:0xf bank_mask:0xf
	v_add_f32_dpp v102, v102, v102 row_mirror row_mask:0xf bank_mask:0xf
	v_add_f32_dpp v103, v103, v103 row_mirror row_mask:0xf bank_mask:0xf
	v_mov_b32_e32 v2, 0x3727c5ac
	v_fma_f32 v100, v100, s4, v2
	v_fma_f32 v101, v101, s4, v2
	v_fma_f32 v102, v102, s4, v2
	v_fma_f32 v103, v103, s4, v2
	v_mul_f32_e32 v0, 0x4b800000, v100
	v_cmp_gt_f32_e32 vcc, s35, v100
	s_nop 1
	v_cndmask_b32_e32 v0, v100, v0, vcc
	v_rsq_f32_e32 v0, v0
	s_nop 0
	v_mul_f32_e32 v2, 0x45800000, v0
	v_cndmask_b32_e32 v104, v0, v2, vcc
	v_mul_f32_e32 v0, 0x4b800000, v101
	v_cmp_gt_f32_e32 vcc, s35, v101
	s_nop 1
	v_cndmask_b32_e32 v0, v101, v0, vcc
	v_rsq_f32_e32 v0, v0
	s_nop 0
	v_mul_f32_e32 v2, 0x45800000, v0
	v_cndmask_b32_e32 v105, v0, v2, vcc
	v_mul_f32_e32 v0, 0x4b800000, v102
	v_cmp_gt_f32_e32 vcc, s35, v102
	s_nop 1
	v_cndmask_b32_e32 v0, v102, v0, vcc
	v_rsq_f32_e32 v0, v0
	s_nop 0
	v_mul_f32_e32 v2, 0x45800000, v0
	v_cndmask_b32_e32 v106, v0, v2, vcc
	v_mul_f32_e32 v0, 0x4b800000, v103
	v_cmp_gt_f32_e32 vcc, s35, v103
	s_nop 1
	v_cndmask_b32_e32 v0, v103, v0, vcc
	v_rsq_f32_e32 v0, v0
	s_nop 0
	v_mul_f32_e32 v2, 0x45800000, v0
	v_cndmask_b32_e32 v107, v0, v2, vcc
	s_waitcnt vmcnt(24)
	v_mul_f32_e32 v8, v8, v104
	v_lshlrev_b32_e32 v48, 16, v48
	v_mul_f32_e32 v8, v8, v48
	v_bfe_u32 v48, v8, 16, 1
	v_add3_u32 v8, v8, v48, s34
	global_store_short_d16_hi v[40:41], v8, off offset:1024
	v_mul_f32_e32 v16, v16, v104
	v_lshlrev_b32_e32 v49, 16, v49
	v_mul_f32_e32 v16, v16, v49
	v_bfe_u32 v49, v16, 16, 1
	v_add3_u32 v16, v16, v49, s34
	global_store_short_d16_hi v[40:41], v16, off offset:1056
	v_mul_f32_e32 v12, v12, v104
	v_lshlrev_b32_e32 v50, 16, v50
	v_mul_f32_e32 v12, v12, v50
	v_bfe_u32 v50, v12, 16, 1
	v_add3_u32 v12, v12, v50, s34
	global_store_short_d16_hi v[40:41], v12, off offset:1088
	v_mul_f32_e32 v36, v36, v104
	v_lshlrev_b32_e32 v51, 16, v51
	v_mul_f32_e32 v36, v36, v51
	v_bfe_u32 v51, v36, 16, 1
	v_add3_u32 v36, v36, v51, s34
	global_store_short_d16_hi v[40:41], v36, off offset:1120
	v_mul_f32_e32 v20, v20, v104
	v_lshlrev_b32_e32 v52, 16, v52
	v_mul_f32_e32 v20, v20, v52
	v_bfe_u32 v52, v20, 16, 1
	v_add3_u32 v20, v20, v52, s34
	global_store_short_d16_hi v[40:41], v20, off offset:1152
	v_mul_f32_e32 v32, v32, v104
	v_lshlrev_b32_e32 v53, 16, v53
	v_mul_f32_e32 v32, v32, v53
	v_bfe_u32 v53, v32, 16, 1
	v_add3_u32 v32, v32, v53, s34
	global_store_short_d16_hi v[40:41], v32, off offset:1184
	v_mul_f32_e32 v24, v24, v104
	v_lshlrev_b32_e32 v54, 16, v54
	v_mul_f32_e32 v24, v24, v54
	v_bfe_u32 v54, v24, 16, 1
	v_add3_u32 v24, v24, v54, s34
	global_store_short_d16_hi v[40:41], v24, off offset:1216
	v_mul_f32_e32 v28, v28, v104
	v_lshlrev_b32_e32 v55, 16, v55
	v_mul_f32_e32 v28, v28, v55
	v_bfe_u32 v55, v28, 16, 1
	v_add3_u32 v28, v28, v55, s34
	global_store_short_d16_hi v[40:41], v28, off offset:1248
	s_waitcnt vmcnt(24)
	v_mul_f32_e32 v9, v9, v105
	v_lshlrev_b32_e32 v56, 16, v56
	v_mul_f32_e32 v9, v9, v56
	v_bfe_u32 v56, v9, 16, 1
	v_add3_u32 v9, v9, v56, s34
	global_store_short_d16_hi v[42:43], v9, off offset:1024
	v_mul_f32_e32 v17, v17, v105
	v_lshlrev_b32_e32 v57, 16, v57
	v_mul_f32_e32 v17, v17, v57
	v_bfe_u32 v57, v17, 16, 1
	v_add3_u32 v17, v17, v57, s34
	global_store_short_d16_hi v[42:43], v17, off offset:1056
	v_mul_f32_e32 v13, v13, v105
	v_lshlrev_b32_e32 v58, 16, v58
	v_mul_f32_e32 v13, v13, v58
	v_bfe_u32 v58, v13, 16, 1
	v_add3_u32 v13, v13, v58, s34
	global_store_short_d16_hi v[42:43], v13, off offset:1088
	v_mul_f32_e32 v37, v37, v105
	v_lshlrev_b32_e32 v59, 16, v59
	v_mul_f32_e32 v37, v37, v59
	v_bfe_u32 v59, v37, 16, 1
	v_add3_u32 v37, v37, v59, s34
	global_store_short_d16_hi v[42:43], v37, off offset:1120
	v_mul_f32_e32 v21, v21, v105
	v_lshlrev_b32_e32 v60, 16, v60
	v_mul_f32_e32 v21, v21, v60
	v_bfe_u32 v60, v21, 16, 1
	v_add3_u32 v21, v21, v60, s34
	global_store_short_d16_hi v[42:43], v21, off offset:1152
	v_mul_f32_e32 v33, v33, v105
	v_lshlrev_b32_e32 v61, 16, v61
	v_mul_f32_e32 v33, v33, v61
	v_bfe_u32 v61, v33, 16, 1
	v_add3_u32 v33, v33, v61, s34
	global_store_short_d16_hi v[42:43], v33, off offset:1184
	v_mul_f32_e32 v25, v25, v105
	v_lshlrev_b32_e32 v62, 16, v62
	v_mul_f32_e32 v25, v25, v62
	v_bfe_u32 v62, v25, 16, 1
	v_add3_u32 v25, v25, v62, s34
	global_store_short_d16_hi v[42:43], v25, off offset:1216
	v_mul_f32_e32 v29, v29, v105
	v_lshlrev_b32_e32 v63, 16, v63
	v_mul_f32_e32 v29, v29, v63
	v_bfe_u32 v63, v29, 16, 1
	v_add3_u32 v29, v29, v63, s34
	global_store_short_d16_hi v[42:43], v29, off offset:1248
	s_waitcnt vmcnt(24)
	v_mul_f32_e32 v10, v10, v106
	v_lshlrev_b32_e32 v64, 16, v64
	v_mul_f32_e32 v10, v10, v64
	v_bfe_u32 v64, v10, 16, 1
	v_add3_u32 v10, v10, v64, s34
	global_store_short_d16_hi v[44:45], v10, off offset:1024
	v_mul_f32_e32 v18, v18, v106
	v_lshlrev_b32_e32 v65, 16, v65
	v_mul_f32_e32 v18, v18, v65
	v_bfe_u32 v65, v18, 16, 1
	v_add3_u32 v18, v18, v65, s34
	global_store_short_d16_hi v[44:45], v18, off offset:1056
	v_mul_f32_e32 v14, v14, v106
	v_lshlrev_b32_e32 v66, 16, v66
	v_mul_f32_e32 v14, v14, v66
	v_bfe_u32 v66, v14, 16, 1
	v_add3_u32 v14, v14, v66, s34
	global_store_short_d16_hi v[44:45], v14, off offset:1088
	v_mul_f32_e32 v38, v38, v106
	v_lshlrev_b32_e32 v67, 16, v67
	v_mul_f32_e32 v38, v38, v67
	v_bfe_u32 v67, v38, 16, 1
	v_add3_u32 v38, v38, v67, s34
	global_store_short_d16_hi v[44:45], v38, off offset:1120
	v_mul_f32_e32 v22, v22, v106
	v_lshlrev_b32_e32 v68, 16, v68
	v_mul_f32_e32 v22, v22, v68
	v_bfe_u32 v68, v22, 16, 1
	v_add3_u32 v22, v22, v68, s34
	global_store_short_d16_hi v[44:45], v22, off offset:1152
	v_mul_f32_e32 v34, v34, v106
	v_lshlrev_b32_e32 v69, 16, v69
	v_mul_f32_e32 v34, v34, v69
	v_bfe_u32 v69, v34, 16, 1
	v_add3_u32 v34, v34, v69, s34
	global_store_short_d16_hi v[44:45], v34, off offset:1184
	v_mul_f32_e32 v26, v26, v106
	v_lshlrev_b32_e32 v70, 16, v70
	v_mul_f32_e32 v26, v26, v70
	v_bfe_u32 v70, v26, 16, 1
	v_add3_u32 v26, v26, v70, s34
	global_store_short_d16_hi v[44:45], v26, off offset:1216
	v_mul_f32_e32 v30, v30, v106
	v_lshlrev_b32_e32 v71, 16, v71
	v_mul_f32_e32 v30, v30, v71
	v_bfe_u32 v71, v30, 16, 1
	v_add3_u32 v30, v30, v71, s34
	global_store_short_d16_hi v[44:45], v30, off offset:1248
	s_waitcnt vmcnt(24)
	v_mul_f32_e32 v11, v11, v107
	v_lshlrev_b32_e32 v72, 16, v72
	v_mul_f32_e32 v11, v11, v72
	v_bfe_u32 v72, v11, 16, 1
	v_add3_u32 v11, v11, v72, s34
	global_store_short_d16_hi v[46:47], v11, off offset:1024
	v_mul_f32_e32 v19, v19, v107
	v_lshlrev_b32_e32 v73, 16, v73
	v_mul_f32_e32 v19, v19, v73
	v_bfe_u32 v73, v19, 16, 1
	v_add3_u32 v19, v19, v73, s34
	global_store_short_d16_hi v[46:47], v19, off offset:1056
	v_mul_f32_e32 v15, v15, v107
	v_lshlrev_b32_e32 v74, 16, v74
	v_mul_f32_e32 v15, v15, v74
	v_bfe_u32 v74, v15, 16, 1
	v_add3_u32 v15, v15, v74, s34
	global_store_short_d16_hi v[46:47], v15, off offset:1088
	v_mul_f32_e32 v39, v39, v107
	v_lshlrev_b32_e32 v75, 16, v75
	v_mul_f32_e32 v39, v39, v75
	v_bfe_u32 v75, v39, 16, 1
	v_add3_u32 v39, v39, v75, s34
	global_store_short_d16_hi v[46:47], v39, off offset:1120
	v_mul_f32_e32 v23, v23, v107
	v_lshlrev_b32_e32 v76, 16, v76
	v_mul_f32_e32 v23, v23, v76
	v_bfe_u32 v76, v23, 16, 1
	v_add3_u32 v23, v23, v76, s34
	global_store_short_d16_hi v[46:47], v23, off offset:1152
	v_mul_f32_e32 v35, v35, v107
	v_lshlrev_b32_e32 v77, 16, v77
	v_mul_f32_e32 v35, v35, v77
	v_bfe_u32 v77, v35, 16, 1
	v_add3_u32 v35, v35, v77, s34
	global_store_short_d16_hi v[46:47], v35, off offset:1184
	v_mul_f32_e32 v27, v27, v107
	v_lshlrev_b32_e32 v78, 16, v78
	v_mul_f32_e32 v27, v27, v78
	v_bfe_u32 v78, v27, 16, 1
	v_add3_u32 v27, v27, v78, s34
	global_store_short_d16_hi v[46:47], v27, off offset:1216
	v_mul_f32_e32 v31, v31, v107
	v_lshlrev_b32_e32 v3, 16, v3
	v_mul_f32_e32 v31, v31, v3
	v_bfe_u32 v3, v31, 16, 1
	v_add3_u32 v31, v31, v3, s34
	global_store_short_d16_hi v[46:47], v31, off offset:1248
	s_mov_b64 s[0:1], 0

.LBB0_2064:
	s_or_b64 exec, exec, s[16:17]
	s_add_u32 s0, s6, 0x80000
	s_addc_u32 s1, s7, 0
	v_ashrrev_i32_e32 v3, 31, v2
	v_mov_b32_e32 v40, 0
	s_mov_b64 s[6:7], s[62:63]
	s_mov_b64 s[24:25], s[62:63]
	v_lshl_add_u64 v[42:43], v[2:3], 2, s[0:1]
	s_movk_i32 s4, 0xc20
	s_mov_b32 s8, 0xfffe0000
	v_mov_b32_e32 v41, v40
	v_mov_b32_e32 v16, v40
	v_mov_b32_e32 v17, v40
	v_mov_b32_e32 v24, v40
	v_mov_b32_e32 v25, v40
	v_mov_b32_e32 v32, v40
	v_mov_b32_e32 v33, v40
	s_waitcnt lgkmcnt(0)
	s_barrier
	v_lshlrev_b32_e32 v248, 2, v2
	s_mov_b32 s98, 0
	v_writelane_b32 v255, s98, 62
	s_mov_b64 s[98:99], s[0:1]
	s_branch .Lfd_body_1
.Lfd_ret_1_0:
	v_mov_b32_e32 v16, v165
	v_mov_b32_e32 v17, v166
	v_mov_b32_e32 v24, v167
	v_mov_b32_e32 v25, v168
	v_mov_b32_e32 v32, v169
	v_mov_b32_e32 v33, v170
	v_mov_b32_e32 v40, v171
	v_mov_b32_e32 v41, v172
.LBB0_2065:
	s_add_i32 s4, s4, 16
	s_mov_b64 s[12:13], 0x8000
	v_lshl_add_u64 v[42:43], v[42:43], 0, s[12:13]
	s_addk_i32 s8, 0x2000
	s_cmp_eq_u32 s8, 0
	s_cbranch_scc0 .LBB0_2065
	v_cvt_f32_i32_e32 v0, s77
	s_sub_i32 s8, s21, s77
	s_and_b64 s[2:3], s[2:3], exec
	v_div_scale_f32 v8, s[2:3], v58, v58, -v0
	v_rcp_f32_e32 v9, v8
	v_div_scale_f32 v10, vcc, -v0, v58, -v0
	s_cselect_b32 s2, 0x200000, 0
	v_fma_f32 v11, -v8, v9, 1.0
	v_fmac_f32_e32 v9, v11, v9
	v_mul_f32_e32 v11, v10, v9
	v_fma_f32 v12, -v8, v11, v10
	v_fmac_f32_e32 v11, v12, v9
	v_fma_f32 v8, -v8, v11, v10
	v_div_fmas_f32 v8, v8, v9, v11
	v_div_fixup_f32 v62, v8, v58, -v0
	v_and_b32_e32 v8, 0x1ff, v2
	s_ashr_i32 s9, s8, 31
	v_cvt_f32_u32_e32 v0, v8
	s_add_u32 s2, s6, s2
	s_addc_u32 s3, s7, 0
	s_add_u32 s48, s2, 0x2480000
	v_mov_b32_e32 v9, 0x40447cbd
	s_addc_u32 s49, s3, 0
	s_lshl_b32 s4, s21, 10
	v_fmamk_f32 v9, v0, 0x3cc4df2d, v9
	v_and_b32_e32 v0, 0x200, v2
	v_bfe_i32 v10, v2, 9, 1
	v_cmp_eq_u32_e64 s[40:41], 0, v0
	v_and_b32_e32 v0, s4, v10
	v_lshlrev_b32_e32 v0, 2, v0
	v_mul_f32_e32 v12, v62, v9
	v_lshl_add_u64 v[10:11], s[48:49], 0, v[0:1]
	v_mul_f32_e32 v0, 0x3fb8aa3b, v12
	v_fma_f32 v13, v12, s50, -v0
	v_rndne_f32_e32 v14, v0
	v_fmac_f32_e32 v13, 0x32a5705f, v12
	v_sub_f32_e32 v0, v0, v14
	v_add_f32_e32 v0, v0, v13
	v_exp_f32_e32 v13, v0
	v_cvt_i32_f32_e32 v14, v14
	s_cmp_lt_i32 s77, 1
	s_cselect_b64 s[22:23], -1, 0
	s_lshl_b64 s[2:3], s[8:9], 11
	v_lshlrev_b32_e32 v0, 2, v8
	v_ldexp_f32 v8, v13, v14
	v_cmp_ngt_f32_e32 vcc, s72, v12
	v_writelane_b32 v255, s2, 23
	v_lshl_add_u64 v[42:43], v[10:11], 0, v[0:1]
	v_cndmask_b32_e32 v8, 0, v8, vcc
	v_cmp_nlt_f32_e32 vcc, s73, v12
	v_writelane_b32 v255, s3, 24
	s_movk_i32 s2, 0x3ff
	v_cndmask_b32_e32 v70, v209, v8, vcc
	v_cmp_lt_u32_e64 s[38:39], s2, v2
	v_mul_f32_e32 v10, v70, v16
	s_and_saveexec_b64 s[2:3], s[38:39]
	s_xor_b64 s[2:3], exec, s[2:3]
	s_cbranch_execz .LBB0_2072
	s_mov_b64 s[6:7], -1
	s_and_b64 vcc, exec, s[22:23]
	s_cbranch_vccz .LBB0_2069
	global_store_dword v[42:43], v1, off
	s_mov_b64 s[6:7], 0

.LBB0_2130:
	s_or_b64 exec, exec, s[26:27]
	s_ashr_i32 s21, s20, 31
	s_lshl_b64 s[20:21], s[20:21], 13
	s_add_u32 s20, s24, s20
	s_addc_u32 s21, s25, s21
	v_lshl_add_u64 v[10:11], v[2:3], 2, s[20:21]
	s_mov_b64 s[20:21], 0xe794000
	v_lshl_add_u64 v[40:41], v[10:11], 0, s[20:21]
	v_add_co_u32_e32 v10, vcc, 0xe794000, v10
	v_mov_b32_e32 v60, 0
	s_nop 0
	v_addc_co_u32_e32 v11, vcc, 0, v11, vcc
	s_movk_i32 s20, 0xc20
	s_mov_b32 s21, 0xfffe0000
	v_mov_b32_e32 v61, v60
	v_mov_b32_e32 v16, v60
	v_mov_b32_e32 v17, v60
	v_mov_b32_e32 v24, v60
	v_mov_b32_e32 v25, v60
	v_mov_b32_e32 v32, v60
	v_mov_b32_e32 v33, v60
	global_store_dword v[10:11], v8, off
	v_lshlrev_b32_e32 v248, 2, v2
	v_add_u32_e32 v248, 0x400, v248
	s_mov_b32 s98, 1
	v_writelane_b32 v255, s98, 62
	s_mov_b64 s[98:99], s[0:1]
	s_branch .Lfd_body_1
.Lfd_ret_1_1:
	v_mov_b32_e32 v16, v165
	v_mov_b32_e32 v17, v166
	v_mov_b32_e32 v24, v167
	v_mov_b32_e32 v25, v168
	v_mov_b32_e32 v32, v169
	v_mov_b32_e32 v33, v170
	v_mov_b32_e32 v60, v171
	v_mov_b32_e32 v61, v172
.LBB0_2131:
	s_add_i32 s20, s20, 16
	s_addk_i32 s21, 0x2000
	s_cmp_lg_u32 s21, 0
	s_cbranch_scc1 .LBB0_2131
	v_add_u32_e32 v12, 0x100, v2
	v_and_b32_e32 v10, 0x1ff, v12
	v_cvt_f32_u32_e32 v3, v10
	v_mov_b32_e32 v8, 0x40447cbd
	v_mov_b32_e32 v9, v1
	v_lshlrev_b32_e32 v10, 2, v10
	v_fmamk_f32 v3, v3, 0x3cc4df2d, v8
	v_bfe_i32 v8, v12, 9, 1
	v_and_b32_e32 v8, s4, v8
	v_lshlrev_b32_e32 v8, 2, v8
	v_lshl_add_u64 v[8:9], s[48:49], 0, v[8:9]
	v_mov_b32_e32 v11, v1
	v_lshl_add_u64 v[8:9], v[8:9], 0, v[10:11]
	v_mul_f32_e32 v10, v62, v3
	s_movk_i32 s20, 0x3ff
	v_mul_f32_e32 v11, 0x3fb8aa3b, v10
	v_cmp_lt_u32_e64 s[42:43], s20, v12
	v_fma_f32 v12, v10, s77, -v11
	v_rndne_f32_e32 v13, v11
	v_fmac_f32_e32 v12, 0x32a5705f, v10
	v_sub_f32_e32 v11, v11, v13
	v_add_f32_e32 v11, v11, v12
	v_exp_f32_e32 v11, v11
	v_cvt_i32_f32_e32 v12, v13
	v_cmp_ngt_f32_e32 vcc, s72, v10
	v_ldexp_f32 v11, v11, v12
	s_nop 0
	v_cndmask_b32_e32 v11, 0, v11, vcc
	v_cmp_nlt_f32_e32 vcc, s73, v10
	s_nop 1
	v_cndmask_b32_e32 v10, v209, v11, vcc
	v_mul_f32_e32 v11, v10, v16
	v_cndmask_b32_e64 v10, 0, 1, s[22:23]
	v_cmp_ne_u32_e64 s[38:39], 1, v10
	s_and_saveexec_b64 s[20:21], s[42:43]
	s_xor_b64 s[20:21], exec, s[20:21]
	s_cbranch_execz .LBB0_2138
	s_and_b64 vcc, exec, s[38:39]
	s_mov_b64 s[22:23], -1
	s_cbranch_vccnz .LBB0_2135
	s_mov_b64 s[22:23], 0
	global_store_dword v[8:9], v1, off

.LBB0_2196:
	s_or_b64 exec, exec, s[20:21]
	v_mov_b32_e32 v60, 0
	s_movk_i32 s20, 0xc20
	s_mov_b32 s21, 0xfffe0000
	v_mov_b32_e32 v61, v60
	v_mov_b32_e32 v16, v60
	v_mov_b32_e32 v17, v60
	v_mov_b32_e32 v24, v60
	v_mov_b32_e32 v25, v60
	v_mov_b32_e32 v32, v60
	v_mov_b32_e32 v33, v60
	global_store_dword v[40:41], v10, off offset:1024
	v_lshlrev_b32_e32 v248, 2, v2
	v_add_u32_e32 v248, 0x800, v248
	s_mov_b32 s98, 2
	v_writelane_b32 v255, s98, 62
	s_mov_b64 s[98:99], s[0:1]
	s_branch .Lfd_body_1

.LBB0_2197:
	s_add_i32 s20, s20, 16
	s_addk_i32 s21, 0x2000
	s_cmp_lg_u32 s21, 0
	s_cbranch_scc1 .LBB0_2197
	v_mov_b32_e32 v8, s4
	v_cndmask_b32_e64 v8, 0, v8, s[40:41]
	v_lshlrev_b32_e32 v8, 2, v8
	v_mov_b32_e32 v9, v1
	v_add_u32_e32 v3, 0x200, v2
	v_lshl_add_u64 v[8:9], s[48:49], 0, v[8:9]
	s_movk_i32 s20, 0x3ff
	v_lshl_add_u64 v[8:9], v[8:9], 0, v[0:1]
	v_cmp_lt_u32_e64 s[40:41], s20, v3
	v_mul_f32_e32 v10, v70, v16
	s_and_saveexec_b64 s[20:21], s[40:41]
	s_xor_b64 s[20:21], exec, s[20:21]
	s_cbranch_execz .LBB0_2204
	s_and_b64 vcc, exec, s[38:39]
	s_mov_b64 s[22:23], -1
	s_cbranch_vccnz .LBB0_2201
	s_mov_b64 s[22:23], 0
	global_store_dword v[8:9], v1, off

.LBB0_2262:
	s_or_b64 exec, exec, s[20:21]
	v_mov_b32_e32 v60, 0
	s_movk_i32 s20, 0xc20
	s_mov_b32 s21, 0xfffe0000
	v_mov_b32_e32 v61, v60
	v_mov_b32_e32 v16, v60
	v_mov_b32_e32 v17, v60
	v_mov_b32_e32 v24, v60
	v_mov_b32_e32 v25, v60
	v_mov_b32_e32 v32, v60
	v_mov_b32_e32 v33, v60
	global_store_dword v[40:41], v3, off offset:2048
	v_lshlrev_b32_e32 v248, 2, v2
	v_add_u32_e32 v248, 0xc00, v248
	s_mov_b32 s98, 3
	v_writelane_b32 v255, s98, 62
	s_mov_b64 s[98:99], s[0:1]
	s_branch .Lfd_body_1

.LBB0_2263:
	s_add_i32 s20, s20, 16
	s_addk_i32 s21, 0x2000
	s_cmp_lg_u32 s21, 0
	s_cbranch_scc1 .LBB0_2263
	v_add_u32_e32 v12, 0x300, v2
	v_and_b32_e32 v10, 0x1ff, v12
	v_cvt_f32_u32_e32 v3, v10
	v_mov_b32_e32 v8, 0x40447cbd
	v_mov_b32_e32 v9, v1
	v_lshlrev_b32_e32 v10, 2, v10
	v_fmamk_f32 v3, v3, 0x3cc4df2d, v8
	v_bfe_i32 v8, v12, 9, 1
	v_and_b32_e32 v8, s4, v8
	v_lshlrev_b32_e32 v8, 2, v8
	v_lshl_add_u64 v[8:9], s[48:49], 0, v[8:9]
	v_mov_b32_e32 v11, v1
	v_lshl_add_u64 v[8:9], v[8:9], 0, v[10:11]
	v_mul_f32_e32 v10, v62, v3
	s_movk_i32 s20, 0x3ff
	v_mul_f32_e32 v11, 0x3fb8aa3b, v10
	v_cmp_lt_u32_e64 s[40:41], s20, v12
	v_fma_f32 v12, v10, s77, -v11
	v_rndne_f32_e32 v13, v11
	v_fmac_f32_e32 v12, 0x32a5705f, v10
	v_sub_f32_e32 v11, v11, v13
	v_add_f32_e32 v11, v11, v12
	v_exp_f32_e32 v11, v11
	v_cvt_i32_f32_e32 v12, v13
	v_cmp_ngt_f32_e32 vcc, s72, v10
	v_ldexp_f32 v11, v11, v12
	s_nop 0
	v_cndmask_b32_e32 v11, 0, v11, vcc
	v_cmp_nlt_f32_e32 vcc, s73, v10
	s_nop 1
	v_cndmask_b32_e32 v10, v209, v11, vcc
	v_mul_f32_e32 v11, v10, v16
	s_and_saveexec_b64 s[20:21], s[40:41]
	s_xor_b64 s[20:21], exec, s[20:21]
	s_cbranch_execz .LBB0_2270
	s_and_b64 vcc, exec, s[38:39]
	s_mov_b64 s[22:23], -1
	s_cbranch_vccnz .LBB0_2267
	s_mov_b64 s[22:23], 0
	global_store_dword v[8:9], v1, off

.LBB0_2328:
	s_or_b64 exec, exec, s[20:21]
	v_mov_b32_e32 v60, 0
	s_movk_i32 s20, 0xc20
	s_mov_b32 s21, 0xfffe0000
	v_mov_b32_e32 v61, v60
	v_mov_b32_e32 v16, v60
	v_mov_b32_e32 v17, v60
	v_mov_b32_e32 v24, v60
	v_mov_b32_e32 v25, v60
	v_mov_b32_e32 v32, v60
	v_mov_b32_e32 v33, v60
	global_store_dword v[40:41], v10, off offset:3072
	v_lshlrev_b32_e32 v248, 2, v2
	v_add_u32_e32 v248, 0x1000, v248
	s_mov_b32 s98, 4
	v_writelane_b32 v255, s98, 62
	s_mov_b64 s[98:99], s[0:1]
	s_branch .Lfd_body_1

.LBB0_2329:
	s_add_i32 s20, s20, 16
	s_addk_i32 s21, 0x2000
	s_cmp_lg_u32 s21, 0
	s_cbranch_scc1 .LBB0_2329
	s_movk_i32 s20, 0xfc00
	v_cmp_gt_u32_e64 s[40:41], s20, v2
	v_mul_f32_e32 v8, v70, v16
	s_and_saveexec_b64 s[20:21], s[40:41]
	s_xor_b64 s[20:21], exec, s[20:21]
	s_cbranch_execz .LBB0_2336
	s_and_b64 vcc, exec, s[38:39]
	s_mov_b64 s[22:23], -1
	s_cbranch_vccnz .LBB0_2333
	s_mov_b64 s[22:23], 0
	global_store_dword v[42:43], v1, off

.LBB0_2394:
	s_or_b64 exec, exec, s[20:21]
	v_add_co_u32_e32 v8, vcc, 0x1000, v40
	v_mov_b32_e32 v42, 0
	s_mov_b32 s20, 0
	v_addc_co_u32_e32 v9, vcc, 0, v41, vcc
	v_add_u32_e32 v44, 0x1d00, v2
	v_mov_b32_e32 v43, v42
	v_mov_b32_e32 v16, v42
	v_mov_b32_e32 v17, v42
	v_mov_b32_e32 v24, v42
	v_mov_b32_e32 v25, v42
	v_mov_b32_e32 v32, v42
	v_mov_b32_e32 v33, v42
	global_store_dword v[8:9], v3, off
	v_lshlrev_b32_e32 v248, 2, v2
	v_add_u32_e32 v248, 0x1400, v248
	s_mov_b32 s98, 5
	v_writelane_b32 v255, s98, 62
	s_mov_b64 s[98:99], s[0:1]
	s_branch .Lfd_body_1
.Lfd_ret_1_5:
	v_mov_b32_e32 v16, v165
	v_mov_b32_e32 v17, v166
	v_mov_b32_e32 v24, v167
	v_mov_b32_e32 v25, v168
	v_mov_b32_e32 v32, v169
	v_mov_b32_e32 v33, v170
	v_mov_b32_e32 v42, v171
	v_mov_b32_e32 v43, v172
.LBB0_2395:
	s_add_i32 s20, s20, 16
	s_cmpk_lg_i32 s20, 0x100
	v_add_u32_e32 v44, 0x2000, v44
	s_cbranch_scc1 .LBB0_2395
	v_add_u32_e32 v3, 0x500, v2
	v_and_b32_e32 v11, 0x1ff, v3
	v_cvt_f32_u32_e32 v8, v11
	v_mov_b32_e32 v9, 0x40447cbd
	s_movk_i32 s20, 0x3ff
	v_cmp_lt_u32_e64 s[40:41], s20, v3
	v_fmamk_f32 v10, v8, 0x3cc4df2d, v9
	v_bfe_i32 v8, v3, 9, 1
	v_and_b32_e32 v8, s4, v8
	v_lshlrev_b32_e32 v8, 2, v8
	v_mov_b32_e32 v9, v1
	v_mul_f32_e32 v3, v62, v10
	v_lshl_add_u64 v[8:9], s[48:49], 0, v[8:9]
	v_lshlrev_b32_e32 v12, 2, v11
	v_mov_b32_e32 v13, v1
	v_mul_f32_e32 v11, 0x3fb8aa3b, v3
	v_lshl_add_u64 v[8:9], v[8:9], 0, v[12:13]
	v_fma_f32 v12, v3, s77, -v11
	v_rndne_f32_e32 v13, v11
	v_fmac_f32_e32 v12, 0x32a5705f, v3
	v_sub_f32_e32 v11, v11, v13
	v_add_f32_e32 v11, v11, v12
	v_exp_f32_e32 v11, v11
	v_cvt_i32_f32_e32 v12, v13
	v_cmp_ngt_f32_e32 vcc, s72, v3
	v_ldexp_f32 v11, v11, v12
	s_nop 0
	v_cndmask_b32_e32 v11, 0, v11, vcc
	v_cmp_nlt_f32_e32 vcc, s73, v3
	s_nop 1
	v_cndmask_b32_e32 v3, v209, v11, vcc
	v_mul_f32_e32 v11, v3, v16
	s_and_saveexec_b64 s[20:21], s[40:41]
	s_xor_b64 s[20:21], exec, s[20:21]
	s_cbranch_execz .LBB0_2402
	s_and_b64 vcc, exec, s[38:39]
	s_mov_b64 s[22:23], -1
	s_cbranch_vccnz .LBB0_2399
	s_mov_b64 s[22:23], 0
	global_store_dword v[8:9], v1, off

.LBB0_2460:
	s_or_b64 exec, exec, s[20:21]
	v_add_co_u32_e32 v8, vcc, 0x1000, v40
	v_mov_b32_e32 v42, 0
	s_mov_b32 s20, 0
	v_addc_co_u32_e32 v9, vcc, 0, v41, vcc
	v_add_u32_e32 v44, 0x1e00, v2
	v_mov_b32_e32 v43, v42
	v_mov_b32_e32 v16, v42
	v_mov_b32_e32 v17, v42
	v_mov_b32_e32 v24, v42
	v_mov_b32_e32 v25, v42
	v_mov_b32_e32 v32, v42
	v_mov_b32_e32 v33, v42
	global_store_dword v[8:9], v3, off offset:1024
	v_lshlrev_b32_e32 v248, 2, v2
	v_add_u32_e32 v248, 0x1800, v248
	s_mov_b32 s98, 6
	v_writelane_b32 v255, s98, 62
	s_mov_b64 s[98:99], s[0:1]
	s_branch .Lfd_body_1

.LBB0_2461:
	s_add_i32 s20, s20, 16
	s_cmpk_lg_i32 s20, 0x100
	v_add_u32_e32 v44, 0x2000, v44
	s_cbranch_scc1 .LBB0_2461
	v_add_u32_e32 v3, 0x600, v2
	v_bfe_i32 v8, v3, 9, 1
	v_and_b32_e32 v8, s4, v8
	v_lshlrev_b32_e32 v8, 2, v8
	v_mov_b32_e32 v9, v1
	v_lshl_add_u64 v[8:9], s[48:49], 0, v[8:9]
	s_movk_i32 s20, 0x3ff
	v_lshl_add_u64 v[8:9], v[8:9], 0, v[0:1]
	v_cmp_lt_u32_e64 s[40:41], s20, v3
	v_mul_f32_e32 v3, v70, v16
	s_and_saveexec_b64 s[20:21], s[40:41]
	s_xor_b64 s[20:21], exec, s[20:21]
	s_cbranch_execz .LBB0_2468
	s_and_b64 vcc, exec, s[38:39]
	s_mov_b64 s[22:23], -1
	s_cbranch_vccnz .LBB0_2465
	s_mov_b64 s[22:23], 0
	global_store_dword v[8:9], v1, off

.LBB0_2526:
	s_or_b64 exec, exec, s[20:21]
	v_add_co_u32_e32 v8, vcc, 0x1000, v40
	v_mov_b32_e32 v42, 0
	s_mov_b32 s20, 0
	v_addc_co_u32_e32 v9, vcc, 0, v41, vcc
	v_add_u32_e32 v44, 0x1f00, v2
	v_mov_b32_e32 v43, v42
	v_mov_b32_e32 v16, v42
	v_mov_b32_e32 v17, v42
	v_mov_b32_e32 v24, v42
	v_mov_b32_e32 v25, v42
	v_mov_b32_e32 v32, v42
	v_mov_b32_e32 v33, v42
	global_store_dword v[8:9], v0, off offset:2048
	v_lshlrev_b32_e32 v248, 2, v2
	v_add_u32_e32 v248, 0x1c00, v248
	s_mov_b32 s98, 7
	v_writelane_b32 v255, s98, 62
	s_mov_b64 s[98:99], s[0:1]
	s_branch .Lfd_body_1

.LBB0_2527:
	s_add_i32 s20, s20, 16
	s_cmpk_lg_i32 s20, 0x100
	v_add_u32_e32 v44, 0x2000, v44
	s_cbranch_scc1 .LBB0_2527
	v_add_u32_e32 v9, 0x700, v2
	v_and_b32_e32 v10, 0x1ff, v9
	v_cvt_f32_u32_e32 v0, v10
	v_mov_b32_e32 v2, 0x40447cbd
	s_movk_i32 s0, 0x3ff
	v_cmp_lt_u32_e64 s[40:41], s0, v9
	v_fmamk_f32 v8, v0, 0x3cc4df2d, v2
	v_bfe_i32 v0, v9, 9, 1
	v_and_b32_e32 v0, s4, v0
	v_lshlrev_b32_e32 v0, 2, v0
	v_lshl_add_u64 v[2:3], s[48:49], 0, v[0:1]
	v_lshlrev_b32_e32 v0, 2, v10
	v_lshl_add_u64 v[2:3], v[2:3], 0, v[0:1]
	v_mul_f32_e32 v0, v62, v8
	v_mul_f32_e32 v9, 0x3fb8aa3b, v0
	v_fma_f32 v10, v0, s77, -v9
	v_rndne_f32_e32 v11, v9
	v_fmac_f32_e32 v10, 0x32a5705f, v0
	v_sub_f32_e32 v9, v9, v11
	v_add_f32_e32 v9, v9, v10
	v_exp_f32_e32 v9, v9
	v_cvt_i32_f32_e32 v10, v11
	v_cmp_ngt_f32_e32 vcc, s72, v0
	v_ldexp_f32 v9, v9, v10
	s_nop 0
	v_cndmask_b32_e32 v9, 0, v9, vcc
	v_cmp_nlt_f32_e32 vcc, s73, v0
	s_nop 1
	v_cndmask_b32_e32 v0, v209, v9, vcc
	v_mul_f32_e32 v9, v0, v16
	s_and_saveexec_b64 s[0:1], s[40:41]
	s_xor_b64 s[0:1], exec, s[0:1]
	s_cbranch_execz .LBB0_2534
	s_and_b64 vcc, exec, s[38:39]
	s_mov_b64 s[20:21], -1
	s_cbranch_vccnz .LBB0_2531
	s_mov_b64 s[20:21], 0
	global_store_dword v[2:3], v1, off
